# QKV projection GEMM: per-tile K loop restricted to the non-zero block of the block-diagonal weight (structural zeros skipped); paired LDS waits in attention
# baseline (speedup 1.0000x reference)
;     __host__ __device__ bool next(int i, Unit& u) const {
;         const long L = (long)i * G + c; if (L >= nwg) return false;
;         int wgid = (int)L; { const int q = nwg / NXCD, r = nwg % NXCD, xcd = wgid % NXCD, off = wgid / NXCD; wgid = (xcd < r ? xcd * (q + 1) : r * (q + 1) + (xcd - r) * q) + off; }
;         const int nig = WGM * nN, gid = wgid / nig, fm = gid * WGM, gsz = (nM - fm) < WGM ? (nM - fm) : WGM;
; template <class Epi, class Sched, bool ALIGN_EPI = false, bool SP2 = false>
; __device__ __forceinline__ void gemm_phase(PG8_LAS unsigned char* lds, const Gemm g, const Sched& S, const Epi& E) {
;     ...
;     const int tid = tid_, wid = __builtin_amdgcn_readfirstlane(tid >> 6), lane = tid & 63, wr = wid >> 2, wc = wid & 3, fr = lane & 15, fq = lane >> 4;
;     const int K = g.K, nt = K / BK;
;     unsigned voffA[2], voffB[2];
; #pragma unroll
;     for (int i = 0; i < 2; ++i) { int R, C; stage_rc(tid * 16 + i * 8192, R, C); const int Rb = Epi::PERM ? ((R & ~31) + perm32(R & 31)) : R;
;         voffA[i] = (unsigned)(R * K + C) * 2u; voffB[i] = (unsigned)(Rb * K + C) * 2u; }
;     const size_t kstep = (size_t)(BK * 2);
;     const size_t hstep = (size_t)HALF * K * 2;
;     const size_t tstep = 2 * hstep;
;     const unsigned ldsw = (unsigned)wid * 1024u;
;     const int aoff = lds_byte(wr * 64 + fr, fq * 8), boff = lds_byte(wc * 32 + fr, fq * 8);
;     ...
;     Unit cur, nxt; int ui = 0;
;     if (!S.next(0, cur)) return;
;     f32x4 acc[2][2][4][2];
; #pragma unroll
;     for (int a = 0; a < 2; ++a)
; #pragma unroll
;         for (int b = 0; b < 2; ++b)
; #pragma unroll
;             for (int m = 0; m < 4; ++m)
; #pragma unroll
;                 for (int n = 0; n < 2; ++n) acc[a][b][m][n] = (f32x4){0.f, 0.f, 0.f, 0.f};
;     bf16x8 At[4][2], B0[2][2], B1[2][2];
;     const char* cA = (const char*)g.A + (size_t)cur.pm * tstep; const char* cB = (const char*)g.Bt + (size_t)cur.pn * tstep;
;     S.a_ready(cur);
;     if constexpr (SP2) {
;         PG8_STAGE(PG8_SB(0, 0), cB, voffB); PG8_STAGE(PG8_SB(0, 1), cB + hstep, voffB); PG8_STAGE(PG8_SA(0, 0), cA, voffA); PG8_STAGE(PG8_SA(0, 1), cA + hstep, voffA);
;         if (wr == 1) PG8_BAR;
;         PG8_WAIT_V(2); PG8_BAR;
;         PG8_STAGE(PG8_SB(1, 0), cB + kstep, voffB); PG8_STAGE(PG8_SA(1, 0), cA + kstep, voffA); PG8_STAGE(PG8_SB(1, 1), cB + hstep + kstep, voffB);
;         PG8_WAIT_V(6); PG8_BAR;
.LBB0_576:
	s_mov_b64 s[8:9], s[84:85]
	s_load_dword s0, s[8:9], 0x120
	s_add_i32 s1, s63, 4
	s_waitcnt lgkmcnt(0)
	s_cmp_lt_i32 s1, s0
	s_cbranch_scc1 .LBB0_666
	s_load_dword s0, s[8:9], 0x124
	s_waitcnt lgkmcnt(0)
	s_cmp_ge_i32 s1, s0
	s_cbranch_scc1 .LBB0_666
	v_mov_b32_e32 v1, v180
	s_load_dwordx2 s[12:13], s[8:9], 0x118
	s_movk_i32 s8, 0x180
	s_movk_i32 s1, 0x700
	s_ashr_i32 s2, s1, 31
	s_lshr_b32 s2, s2, 24
	s_add_i32 s1, s1, s2
	s_ashr_i32 s6, s1, 8
	s_lshl_b32 s14, s6, 7
	v_mov_b32_e32 v20, v180
	s_cmp_ge_i32 s73, s14
	v_readfirstlane_b32 s10, v20
	s_cbranch_scc1 .LBB0_600
	v_lshlrev_b32_e32 v1, 4, v20
	v_add_u32_e32 v2, 0x2000, v1
	v_ashrrev_i32_e32 v3, 31, v2
	v_lshrrev_b32_e32 v3, 22, v3
	v_add_u32_e32 v3, v2, v3
	v_ashrrev_i32_e32 v3, 10, v3
	v_mul_i32_i24_e32 v4, 0x400, v3
	v_sub_u32_e32 v2, v2, v4
	v_lshrrev_b32_e32 v4, 4, v2
	v_bitop3_b32 v2, v4, v2, 32 bitop3:0x6c
	v_ashrrev_i32_e32 v4, 31, v2
	s_waitcnt lgkmcnt(0)
	s_add_u32 s1, s12, 0x18600000
	v_lshrrev_b32_e32 v4, 26, v4
	s_addc_u32 s2, s13, 0
	s_mul_i32 s7, s81, 0x2800000
	v_add_u32_e32 v4, v2, v4
	v_lshlrev_b32_e32 v6, 3, v3
	s_add_u32 s7, s12, s7
	v_ashrrev_i32_e32 v5, 6, v4
	v_and_b32_e32 v6, -16, v6
	v_lshlrev_b32_e32 v3, 5, v3
	s_addc_u32 s9, s13, 0
	v_add_u32_e32 v6, v5, v6
	v_and_b32_e32 v14, 32, v3
	v_and_b32_e32 v3, 0xc0, v4
	s_add_u32 s36, s7, 0x1500000
	v_and_b32_e32 v5, 3, v5
	s_mov_b32 s7, 0x7fffffe0
	v_lshrrev_b32_e32 v7, 2, v6
	v_lshlrev_b32_e32 v8, 1, v6
	v_sub_u32_e32 v2, v2, v3
	v_and_or_b32 v5, v6, s7, v5
	v_and_b32_e32 v7, 4, v7
	v_and_b32_e32 v8, 24, v8
	v_ashrrev_i16_sdwa v2, v155, sext(v2) dst_sel:DWORD dst_unused:UNUSED_PAD src0_sel:DWORD src1_sel:BYTE_0
	v_or3_b32 v5, v5, v7, v8
	v_bfe_i32 v15, v2, 0, 16
	v_mul_lo_u32 v5, v5, s8
	v_add_u32_e32 v2, v14, v15
	v_mul_lo_u32 v16, v6, s8
	v_add_lshl_u32 v130, v5, v2, 1
	v_add_lshl_u32 v132, v2, v16, 1
	v_bfe_i32 v2, v20, 27, 1
	v_lshrrev_b32_e32 v2, 22, v2
	v_add_u32_e32 v2, v1, v2
	v_and_b32_e32 v2, 0xfffffc00, v2
	v_sub_u32_e32 v1, v1, v2
	v_lshrrev_b32_e32 v2, 4, v1
	v_ashrrev_i32_e32 v4, 31, v20
	v_bitop3_b32 v1, v2, v1, 32 bitop3:0x6c
	v_lshrrev_b32_e32 v4, 26, v4
	v_ashrrev_i32_e32 v2, 31, v1
	v_add_u32_e32 v4, v20, v4
	v_lshrrev_b32_e32 v2, 26, v2
	v_ashrrev_i32_e32 v4, 6, v4
	v_add_u32_e32 v2, v1, v2
	v_lshlrev_b32_e32 v5, 3, v4
	v_ashrrev_i32_e32 v3, 6, v2
	v_and_b32_e32 v5, -16, v5
	v_add_u32_e32 v5, v3, v5
	v_and_b32_e32 v2, 0xc0, v2
	v_and_b32_e32 v3, 3, v3
	v_lshrrev_b32_e32 v6, 2, v5
	v_lshlrev_b32_e32 v7, 1, v5
	v_sub_u32_e32 v1, v1, v2
	v_and_or_b32 v3, v5, s7, v3
	v_and_b32_e32 v6, 4, v6
	v_and_b32_e32 v7, 24, v7
	v_lshlrev_b32_e32 v4, 5, v4
	v_ashrrev_i16_sdwa v1, v155, sext(v1) dst_sel:DWORD dst_unused:UNUSED_PAD src0_sel:DWORD src1_sel:BYTE_0
	s_addc_u32 s37, s9, 0
	v_or3_b32 v3, v3, v6, v7
	v_and_b32_e32 v17, 32, v4
	v_bfe_i32 v18, v1, 0, 16
	s_lshl_b32 s40, s6, 3
	v_mul_lo_u32 v3, v3, s8
	v_add_u32_e32 v1, v17, v18
	v_mul_lo_u32 v19, v5, s8
	s_abs_i32 s42, s40
	v_add_lshl_u32 v134, v3, v1, 1
	v_add_lshl_u32 v136, v1, v19, 1
	v_cvt_f32_u32_e32 v1, s42
	s_lshl_b32 s39, s6, 4
	s_or_b32 s7, s39, s96
	s_mul_i32 s7, s7, s95
	v_rcp_iflag_f32_e32 v1, v1
	s_sub_i32 s21, 0, s42
	s_add_i32 s7, s7, s94
	s_ashr_i32 s20, s7, 31
	v_mul_f32_e32 v1, 0x4f7ffffe, v1
	v_cvt_u32_f32_e32 v1, v1
	s_bfe_i32 s41, s6, 0x1001c
	s_xor_b32 s6, s20, s41
	s_abs_i32 s20, s7
	v_readfirstlane_b32 s43, v1
	s_mul_i32 s21, s21, s43
	s_mul_hi_u32 s21, s43, s21
	s_add_i32 s43, s43, s21
	s_mul_hi_u32 s21, s20, s43
	s_mul_i32 s22, s21, s42
	s_ashr_i32 s11, s10, 6
	s_ashr_i32 s9, s8, 31
	s_sub_i32 s20, s20, s22
	s_ashr_i32 s15, s10, 8
	s_lshl_b64 s[16:17], s[8:9], 8
	s_lshl_b64 s[18:19], s[8:9], 9
	s_lshl_b32 s38, s11, 10
	s_add_i32 s22, s21, 1
	s_sub_i32 s23, s20, s42
	s_cmp_ge_u32 s20, s42
	s_cselect_b32 s21, s22, s21
	s_cselect_b32 s20, s23, s20
	s_add_i32 s22, s21, 1
	s_cmp_ge_u32 s20, s42
	s_cselect_b32 s20, s22, s21
	s_xor_b32 s20, s20, s6
	s_sub_i32 s6, s20, s6
	s_lshl_b32 s20, s6, 3
	s_sub_i32 s21, 0x80, s20
	s_min_i32 s21, s21, 8
	s_abs_i32 s23, s21
	v_cvt_f32_u32_e32 v1, s23
	s_sub_i32 s24, 0, s23
	s_mul_i32 s6, s6, s40
	s_sub_i32 s6, s7, s6
	v_rcp_iflag_f32_e32 v1, v1
	s_abs_i32 s22, s6
	s_xor_b32 s7, s6, s21
	s_ashr_i32 s7, s7, 31
	v_mul_f32_e32 v1, 0x4f7ffffe, v1
	v_cvt_u32_f32_e32 v1, v1
	v_mov_b32_e32 v135, v0
	v_mov_b32_e32 v131, v0
	v_mov_b32_e32 v137, v0
	v_readfirstlane_b32 s25, v1
	s_mul_i32 s24, s24, s25
	s_mul_hi_u32 s24, s25, s24
	s_add_i32 s25, s25, s24
	s_mul_hi_u32 s24, s22, s25
	s_mul_i32 s25, s24, s23
	s_sub_i32 s22, s22, s25
	s_add_i32 s25, s24, 1
	s_sub_i32 s26, s22, s23
	s_cmp_ge_u32 s22, s23
	s_cselect_b32 s24, s25, s24
	s_cselect_b32 s22, s26, s22
	s_add_i32 s25, s24, 1
	s_cmp_ge_u32 s22, s23
	s_cselect_b32 s22, s25, s24
	s_xor_b32 s22, s22, s7
	s_sub_i32 s49, s22, s7
	s_mul_i32 s7, s49, s21
	s_sub_i32 s6, s6, s7
	s_add_i32 s50, s6, s20
	s_ashr_i32 s6, s50, 31
	s_mul_i32 s6, s18, s6
	s_mul_hi_u32 s7, s18, s50
	s_add_i32 s20, s7, s6
	s_lshr_b64 s[6:7], s[8:9], 23
	s_mul_i32 s7, s6, s50
	s_add_i32 s20, s20, s7
	s_ashr_i32 s7, s49, 31
	s_mul_i32 s7, s18, s7
	s_mul_hi_u32 s22, s18, s49
	s_add_i32 s7, s22, s7
	s_mul_i32 s6, s6, s49
	s_add_i32 s7, s7, s6
	s_mul_i32 s6, s18, s49
	s_add_u32 s34, s36, s6
	s_addc_u32 s35, s37, s7
	s_cmp_ge_i32 s49, 3
	s_cselect_b32 s100, 0x200, 0
	s_add_u32 s34, s34, s100
	s_addc_u32 s35, s35, 0
	s_add_i32 s44, s38, 0
	s_add_i32 m0, s44, 0x10000
	s_mul_i32 s21, s18, s50
	global_load_lds_dwordx4 v134, s[34:35]
	s_add_i32 m0, s44, 0x12000
	s_add_u32 s6, s34, s16
	global_load_lds_dwordx4 v130, s[34:35]
	s_addc_u32 s7, s35, s17
	s_add_i32 m0, s44, 0x14000
	v_lshl_add_u64 v[6:7], s[6:7], 0, v[134:135]
	global_load_lds_dwordx4 v134, s[6:7]
	s_add_i32 m0, s44, 0x16000
	s_add_u32 s30, s1, s21
	s_addc_u32 s31, s2, s20
	s_add_u32 s30, s30, s100
	s_addc_u32 s31, s31, 0
	s_add_i32 s45, s44, 0x2000
	v_lshl_add_u64 v[8:9], s[6:7], 0, v[130:131]
	global_load_lds_dwordx4 v130, s[6:7]
	s_mov_b32 m0, s44
	s_add_u32 s6, s30, s16
	global_load_lds_dwordx4 v136, s[30:31]
	s_mov_b32 m0, s45
	s_addc_u32 s7, s31, s17
	s_add_i32 s46, s44, 0x4000
	global_load_lds_dwordx4 v132, s[30:31]
	s_mov_b32 m0, s46
	s_add_i32 s47, s44, 0x6000
	global_load_lds_dwordx4 v136, s[6:7]
	s_mov_b32 m0, s47
	v_mov_b32_e32 v133, v0
	global_load_lds_dwordx4 v132, s[6:7]
	s_cmp_eq_u32 s15, 1
	v_lshl_add_u64 v[2:3], s[34:35], 0, v[134:135]
	v_lshl_add_u64 v[4:5], s[34:35], 0, v[130:131]
	v_lshl_add_u64 v[10:11], s[30:31], 0, v[136:137]
	v_lshl_add_u64 v[12:13], s[30:31], 0, v[132:133]
	s_cselect_b64 s[20:21], -1, 0
	s_cmp_lg_u32 s15, 1
	s_cbranch_scc1 .LBB0_581
	s_barrier

;     __host__ __device__ bool next(int i, Unit& u) const {
;         const long L = (long)i * G + c; if (L >= nwg) return false;
;         int wgid = (int)L; { const int q = nwg / NXCD, r = nwg % NXCD, xcd = wgid % NXCD, off = wgid / NXCD; wgid = (xcd < r ? xcd * (q + 1) : r * (q + 1) + (xcd - r) * q) + off; }
;         const int nig = WGM * nN, gid = wgid / nig, fm = gid * WGM, gsz = (nM - fm) < WGM ? (nM - fm) : WGM;
;         u.pm = fm + ((wgid % nig) % gsz); u.pn = (wgid % nig) / gsz; return true;
;     }
; template <class Epi, class Sched, bool ALIGN_EPI = false, bool SP2 = false>
; __device__ __forceinline__ void gemm_phase(PG8_LAS unsigned char* lds, const Gemm g, const Sched& S, const Epi& E) {
;     ...
;         const bool has_next = S.next(ui + 1, nxt);
;         const char* nA = has_next ? (const char*)g.A + (size_t)nxt.pm * tstep : cA; const char* nB = has_next ? (const char*)g.Bt + (size_t)nxt.pn * tstep : cB;
;         for (int t = 0; t < nt; t += 2) {
;             const bool last = (t == nt - 2);
;             const char* a1 = cA + (size_t)(t + 1) * kstep;
;             const char* a2 = last ? nA : cA + (size_t)(t + 2) * kstep; const char* b2 = last ? nB : cB + (size_t)(t + 2) * kstep;
;             const char* a3 = a2 + kstep; const char* b3 = b2 + kstep;
;             if (last && has_next) S.a_ready(nxt);
.LBB0_584:
	s_cmp_ge_i32 s49, 3
	s_cselect_b32 s48, 2, 4
	s_add_i32 s56, s48, -2
	s_add_i32 s57, s57, 1
	s_mul_i32 s6, s57, s5
	s_mul_hi_u32 s7, s57, s92
	s_add_i32 s7, s7, s6
	s_mul_i32 s6, s57, s92
	s_add_u32 s8, s6, s73
	s_addc_u32 s9, s7, s3
	v_mov_b64_e32 v[2:3], s[14:15]
	v_cmp_ge_i64_e32 vcc, s[8:9], v[2:3]
	v_cmp_lt_i64_e64 s[10:11], s[8:9], v[2:3]
	s_cbranch_vccnz .LBB0_586
	s_ashr_i32 s6, s8, 31
	s_lshr_b32 s6, s6, 29
	s_add_i32 s6, s8, s6
	s_ashr_i32 s7, s6, 3
	s_and_b32 s6, s6, -8
	s_sub_i32 s6, s8, s6
	s_lshr_b32 s8, s6, 31
	s_or_b32 s8, s8, s39
	s_mul_i32 s6, s8, s6
	s_add_i32 s6, s6, s7
	s_abs_i32 s8, s6
	s_mul_hi_u32 s9, s8, s43
	s_mul_i32 s28, s9, s42
	s_ashr_i32 s7, s6, 31
	s_sub_i32 s8, s8, s28
	s_xor_b32 s7, s7, s41
	s_add_i32 s28, s9, 1
	s_sub_i32 s29, s8, s42
	s_cmp_ge_u32 s8, s42
	s_cselect_b32 s9, s28, s9
	s_cselect_b32 s8, s29, s8
	s_add_i32 s28, s9, 1
	s_cmp_ge_u32 s8, s42
	s_cselect_b32 s8, s28, s9
	s_xor_b32 s8, s8, s7
	s_sub_i32 s7, s8, s7
	s_lshl_b32 s8, s7, 3
	s_sub_i32 s9, 0x80, s8
	s_min_i32 s9, s9, 8
	s_abs_i32 s28, s9
	v_cvt_f32_u32_e32 v2, s28
	s_sub_i32 s33, 0, s28
	s_mul_i32 s7, s7, s40
	s_sub_i32 s6, s6, s7
	v_rcp_iflag_f32_e32 v2, v2
	s_abs_i32 s29, s6
	s_xor_b32 s7, s6, s9
	s_ashr_i32 s7, s7, 31
	v_mul_f32_e32 v2, 0x4f7ffffe, v2
	v_cvt_u32_f32_e32 v2, v2
	s_nop 0
	v_readfirstlane_b32 s59, v2
	s_mul_i32 s33, s33, s59
	s_mul_hi_u32 s33, s59, s33
	s_add_i32 s59, s59, s33
	s_mul_hi_u32 s33, s29, s59
	s_mul_i32 s59, s33, s28
	s_sub_i32 s29, s29, s59
	s_add_i32 s59, s33, 1
	s_sub_i32 s60, s29, s28
	s_cmp_ge_u32 s29, s28
	s_cselect_b32 s33, s59, s33
	s_cselect_b32 s29, s60, s29
	s_add_i32 s59, s33, 1
	s_cmp_ge_u32 s29, s28
	s_cselect_b32 s28, s59, s33
	s_xor_b32 s28, s28, s7
	s_sub_i32 s60, s28, s7
	s_mul_i32 s7, s60, s9
	s_sub_i32 s6, s6, s7
	s_add_i32 s64, s6, s8
.LBB0_586:
	s_nop 0
	v_cndmask_b32_e64 v2, 0, 1, s[10:11]
	v_cmp_ne_u32_e64 s[8:9], 1, v2
	s_andn2_b64 vcc, exec, s[10:11]
	s_mov_b64 s[10:11], s[30:31]
	s_cbranch_vccnz .LBB0_588
	s_ashr_i32 s6, s64, 31
	s_mul_hi_u32 s7, s18, s64
	s_mul_i32 s6, s18, s6
	s_add_i32 s6, s7, s6
	s_mul_i32 s7, s19, s64
	s_add_i32 s6, s6, s7
	s_mul_i32 s7, s18, s64
	s_add_u32 s10, s1, s7
	s_addc_u32 s11, s2, s6
	s_cmp_ge_i32 s60, 3
	s_cselect_b32 s100, 0x200, 0
	s_add_u32 s10, s10, s100
	s_addc_u32 s11, s11, 0
.LBB0_588:
	s_and_b64 vcc, exec, s[8:9]
	s_mov_b64 s[28:29], s[34:35]
	s_cbranch_vccnz .LBB0_590
	s_ashr_i32 s6, s60, 31
	s_mul_hi_u32 s7, s18, s60
	s_mul_i32 s6, s18, s6
	s_add_i32 s6, s7, s6
	s_mul_i32 s7, s19, s60
	s_add_i32 s6, s6, s7
	s_mul_i32 s7, s18, s60
	s_add_u32 s28, s36, s7
	s_addc_u32 s29, s37, s6
	s_cmp_ge_i32 s60, 3
	s_cselect_b32 s100, 0x200, 0
	s_add_u32 s28, s28, s100
	s_addc_u32 s29, s29, 0

; template <bool FIRST> __device__ __forceinline__ void partialSM(f32x16& p0, f32x16& p1, float& mhat, f32x16& negm, float& alpha) {
;   float pa = fmaxf(fmaxf(p0[0], p0[1]), p1[0]), pb = fmaxf(fmaxf(p0[2], p0[3]), p1[1]); pa = fmaxf(fmaxf(pa, p1[2]), p1[3]);
; #pragma unroll
;   for (int r = 4; r < 16; r += 4) { pa = fmaxf(fmaxf(pa, p0[r]), p0[r + 1]); pb = fmaxf(fmaxf(pb, p0[r + 2]), p0[r + 3]); pa = fmaxf(fmaxf(pa, p1[r]), p1[r + 1]); pb = fmaxf(fmaxf(pb, p1[r + 2]), p1[r + 3]); }
;   float pmax = fmaxf(pa, pb);
;   { auto rr = __builtin_amdgcn_permlane32_swap(__float_as_uint(pmax), __float_as_uint(pmax), false, false);
;     pmax = fmaxf(__uint_as_float(rr[0]), __uint_as_float(rr[1])); }
;   if (!FIRST && __builtin_expect(__all(pmax <= THRL), 1)) { alpha = 1.f; }
;   else { const float d = FIRST ? pmax : fmaxf(pmax, 0.f); mhat += d; alpha = FIRST ? 1.f : __builtin_amdgcn_exp2f(-d);
; #pragma unroll
;     for (int r = 0; r < 16; ++r) { p0[r] -= d; p1[r] -= d; }
; #pragma unroll
;     for (int r = 0; r < 16; ++r) negm[r] = -mhat; }
; #pragma unroll
;   for (int r = 0; r < 16; ++r) p0[r] = __builtin_amdgcn_exp2f(p0[r]);
; }
; __device__ __forceinline__ void finishSM(f32x16& p0, f32x16& p1, float alpha, float& l_reg, bf16x8& pa0, bf16x8& pa1, bf16x8& pa2, bf16x8& pa3) {
; #pragma unroll
;   for (int r = 0; r < 16; ++r) p1[r] = __builtin_amdgcn_exp2f(p1[r]);
;   float ps = 0;
; #pragma unroll
;   for (int r = 0; r < 16; ++r) ps += p0[r];
; #pragma unroll
;   for (int r = 0; r < 16; ++r) ps += p1[r];
;   { auto rr = __builtin_amdgcn_permlane32_swap(__float_as_uint(ps), __float_as_uint(ps), false, false);
;     ps = __uint_as_float(rr[0]) + __uint_as_float(rr[1]); }
;   l_reg = l_reg * alpha + ps;
;     ...
;   PK4(p0, 0, pa0); PK4(p0, 8, pa1); PK4(p1, 0, pa2); PK4(p1, 8, pa3);
;     ...
; }
; __device__ __forceinline__ void qkt(f32x16& p0, f32x16& p1, const bf16_t* Ks, const bf16x8* qr, const f32x16& negm, int r32, int hi) {
;   p0 = negm; p1 = negm;
; #pragma unroll
;   for (int d0 = 0; d0 < 6; ++d0) { int cb = (d0 * 16 + hi * 8) * 2;
;     bf16x8 b0 = *reinterpret_cast<const bf16x8*>((const char*)Ks + KSWZ(r32, cb));
;     bf16x8 b1 = *reinterpret_cast<const bf16x8*>((const char*)Ks + KSWZ(32 + r32, cb));
;     p0 = __builtin_amdgcn_mfma_f32_32x32x16_bf16(b0, qr[d0], p0, 0, 0, 0);
;     p1 = __builtin_amdgcn_mfma_f32_32x32x16_bf16(b1, qr[d0], p1, 0, 0, 0); }
; }
.Lat_loop:
	ds_read_b128 v[198:201], v142 offset:16384
	ds_read_b128 v[202:205], v142 offset:24576
	ds_read_b128 v[206:209], v143 offset:16384
	ds_read_b128 v[210:213], v143 offset:24576
	s_add_i32 m0, s6, 0
	s_mov_b64 exec, s[20:21]
	global_load_lds_dwordx4 v146, s[14:15]
	s_add_i32 m0, s6, 1024
	s_mov_b64 exec, s[22:23]
	global_load_lds_dwordx4 v147, s[14:15]
	s_add_i32 m0, s7, 32768
	s_mov_b64 exec, -1
	global_load_lds_dwordx4 v149, s[14:15]
	v_add_u32_e32 v146, v146, v148
	v_add_u32_e32 v147, v147, v181
	v_add_u32_e32 v149, 0x38000, v149
	s_waitcnt lgkmcnt(6)
	v_mfma_f32_32x32x16_bf16 v[66:81], v[182:185], v[114:117], v[98:113]
	ds_read_b128 v[182:185], v144 offset:16384
	v_exp_f32_e32 v50, v50
	v_exp_f32_e32 v51, v51
	v_exp_f32_e32 v52, v52
	v_exp_f32_e32 v53, v53
	v_exp_f32_e32 v54, v54
	v_mfma_f32_32x32x16_bf16 v[82:97], v[186:189], v[114:117], v[98:113]
	ds_read_b128 v[186:189], v144 offset:24576
	v_exp_f32_e32 v55, v55
	v_exp_f32_e32 v56, v56
	v_exp_f32_e32 v57, v57
	v_exp_f32_e32 v58, v58
	v_exp_f32_e32 v59, v59
	s_waitcnt lgkmcnt(6)
	v_mfma_f32_32x32x16_bf16 v[66:81], v[190:193], v[118:121], v[66:81]
	ds_read_b128 v[190:193], v145 offset:16384
	v_exp_f32_e32 v60, v60
	v_exp_f32_e32 v61, v61
	v_exp_f32_e32 v62, v62
	v_exp_f32_e32 v63, v63
	v_exp_f32_e32 v64, v64
	v_mfma_f32_32x32x16_bf16 v[82:97], v[194:197], v[118:121], v[82:97]
	ds_read_b128 v[194:197], v145 offset:24576
	v_exp_f32_e32 v65, v65
	v_cvt_pk_bf16_f32 v158, v34, v35
	v_cvt_pk_bf16_f32 v159, v36, v37
	v_cvt_pk_bf16_f32 v160, v38, v39
	v_cvt_pk_bf16_f32 v161, v40, v41
	s_waitcnt lgkmcnt(6)
	v_mfma_f32_32x32x16_bf16 v[66:81], v[198:201], v[122:125], v[66:81]
	ds_read_b64_tr_b16 v[198:199], v150 offset:8192
	ds_read_b64_tr_b16 v[200:201], v150 offset:10240
	v_cvt_pk_bf16_f32 v162, v42, v43
	v_cvt_pk_bf16_f32 v163, v44, v45
	v_cvt_pk_bf16_f32 v164, v46, v47
	v_cvt_pk_bf16_f32 v165, v48, v49
	v_permlane32_swap_b32_e32 v158, v160
	v_mfma_f32_32x32x16_bf16 v[82:97], v[202:205], v[122:125], v[82:97]
	ds_read_b64_tr_b16 v[202:203], v150 offset:8704
	ds_read_b64_tr_b16 v[204:205], v150 offset:10752
	v_permlane32_swap_b32_e32 v159, v161
	v_permlane32_swap_b32_e32 v162, v164
	v_permlane32_swap_b32_e32 v163, v165
	v_add_f32_e32 v214, v214, v50
	v_add_f32_e32 v215, v215, v51
	s_waitcnt lgkmcnt(8)
	v_mfma_f32_32x32x16_bf16 v[66:81], v[206:209], v[126:129], v[66:81]
	ds_read_b64_tr_b16 v[206:207], v150 offset:12288
	ds_read_b64_tr_b16 v[208:209], v150 offset:14336
	v_add_f32_e32 v216, v216, v52
	v_add_f32_e32 v217, v217, v53
	v_add_f32_e32 v214, v214, v54
	v_add_f32_e32 v215, v215, v55
	v_add_f32_e32 v216, v216, v56
	v_mfma_f32_32x32x16_bf16 v[82:97], v[210:213], v[126:129], v[82:97]
	ds_read_b64_tr_b16 v[210:211], v150 offset:12800
	ds_read_b64_tr_b16 v[212:213], v150 offset:14848
	v_add_f32_e32 v217, v217, v57
	v_add_f32_e32 v214, v214, v58
	v_add_f32_e32 v215, v215, v59
	v_add_f32_e32 v216, v216, v60
	v_add_f32_e32 v217, v217, v61
	s_waitcnt lgkmcnt(10)
	v_mfma_f32_32x32x16_bf16 v[66:81], v[182:185], v[130:133], v[66:81]
	ds_read_b64_tr_b16 v[182:183], v150 offset:0
	ds_read_b64_tr_b16 v[184:185], v150 offset:2048
	v_add_f32_e32 v214, v214, v62
	v_add_f32_e32 v215, v215, v63
	v_add_f32_e32 v216, v216, v64
	v_add_f32_e32 v217, v217, v65
	v_add_f32_e32 v214, v214, v215
	v_mfma_f32_32x32x16_bf16 v[82:97], v[186:189], v[130:133], v[82:97]
	ds_read_b64_tr_b16 v[186:187], v150 offset:512
	ds_read_b64_tr_b16 v[188:189], v150 offset:2560
	v_add_f32_e32 v216, v216, v217
	v_add_f32_e32 v214, v214, v216
	v_add_f32_e32 v174, v174, v214
	v_cvt_pk_bf16_f32 v166, v50, v51
	v_cvt_pk_bf16_f32 v167, v52, v53
	s_waitcnt lgkmcnt(12)
	v_mfma_f32_32x32x16_bf16 v[66:81], v[190:193], v[134:137], v[66:81]
	ds_read_b64_tr_b16 v[190:191], v150 offset:4096
	ds_read_b64_tr_b16 v[192:193], v150 offset:6144
	v_cvt_pk_bf16_f32 v168, v54, v55
	v_cvt_pk_bf16_f32 v169, v56, v57
	v_cvt_pk_bf16_f32 v170, v58, v59
	v_cvt_pk_bf16_f32 v171, v60, v61
	v_cvt_pk_bf16_f32 v172, v62, v63
	v_mfma_f32_32x32x16_bf16 v[82:97], v[194:197], v[134:137], v[82:97]
	ds_read_b64_tr_b16 v[194:195], v150 offset:4608
	s_waitcnt lgkmcnt(14)
	ds_read_b64_tr_b16 v[196:197], v150 offset:6656
	v_cvt_pk_bf16_f32 v173, v64, v65
	v_permlane32_swap_b32_e32 v166, v168
	v_permlane32_swap_b32_e32 v167, v169
	v_permlane32_swap_b32_e32 v170, v172
	v_permlane32_swap_b32_e32 v171, v173
	s_waitcnt lgkmcnt(4)
	v_mfma_f32_32x32x16_bf16 v[2:17], v[158:161], v[182:185], v[2:17]
	ds_read_b128 v[182:185], v140 offset:32768
	v_max3_f32 v177, v66, v67, v68
	v_max3_f32 v178, v69, v70, v71
	v_max3_f32 v177, v177, v72, v73
	v_mfma_f32_32x32x16_bf16 v[18:33], v[158:161], v[186:189], v[18:33]
	ds_read_b128 v[186:189], v140 offset:40960
	v_max3_f32 v178, v178, v74, v75
	v_max3_f32 v177, v177, v76, v77
	v_max3_f32 v178, v178, v78, v79
	v_max3_f32 v177, v177, v80, v81
	v_max3_f32 v178, v178, v82, v83
	v_max3_f32 v177, v177, v84, v85
	s_waitcnt lgkmcnt(2)
	v_mfma_f32_32x32x16_bf16 v[2:17], v[162:165], v[190:193], v[2:17]
	ds_read_b128 v[190:193], v141 offset:32768
	v_max3_f32 v178, v178, v86, v87
	v_max3_f32 v177, v177, v88, v89
	v_max3_f32 v178, v178, v90, v91
	v_max3_f32 v177, v177, v92, v93
	v_max3_f32 v178, v178, v94, v95
	v_max3_f32 v177, v177, v96, v97
	v_mfma_f32_32x32x16_bf16 v[18:33], v[162:165], v[194:197], v[18:33]
	ds_read_b128 v[194:197], v141 offset:40960
	v_max_f32_e32 v177, v177, v178
	v_mov_b32_e32 v178, v177
	s_nop 1
	v_permlane32_swap_b32_e32 v177, v178
	v_max_f32_e32 v177, v177, v178
	v_cmp_ge_f32_e32 vcc, 0x4138aa3b, v177
	s_cmp_eq_u64 vcc, exec
	s_cbranch_scc0 .Lat_rare1_2

; template <bool FIRST> __device__ __forceinline__ void partialSM(f32x16& p0, f32x16& p1, float& mhat, f32x16& negm, float& alpha) {
;   float pa = fmaxf(fmaxf(p0[0], p0[1]), p1[0]), pb = fmaxf(fmaxf(p0[2], p0[3]), p1[1]); pa = fmaxf(fmaxf(pa, p1[2]), p1[3]);
; #pragma unroll
;   for (int r = 4; r < 16; r += 4) { pa = fmaxf(fmaxf(pa, p0[r]), p0[r + 1]); pb = fmaxf(fmaxf(pb, p0[r + 2]), p0[r + 3]); pa = fmaxf(fmaxf(pa, p1[r]), p1[r + 1]); pb = fmaxf(fmaxf(pb, p1[r + 2]), p1[r + 3]); }
;   float pmax = fmaxf(pa, pb);
;   { auto rr = __builtin_amdgcn_permlane32_swap(__float_as_uint(pmax), __float_as_uint(pmax), false, false);
;     pmax = fmaxf(__uint_as_float(rr[0]), __uint_as_float(rr[1])); }
;   if (!FIRST && __builtin_expect(__all(pmax <= THRL), 1)) { alpha = 1.f; }
;   else { const float d = FIRST ? pmax : fmaxf(pmax, 0.f); mhat += d; alpha = FIRST ? 1.f : __builtin_amdgcn_exp2f(-d);
; #pragma unroll
;     for (int r = 0; r < 16; ++r) { p0[r] -= d; p1[r] -= d; }
; #pragma unroll
;     for (int r = 0; r < 16; ++r) negm[r] = -mhat; }
; #pragma unroll
;   for (int r = 0; r < 16; ++r) p0[r] = __builtin_amdgcn_exp2f(p0[r]);
; }
; __device__ __forceinline__ void finishSM(f32x16& p0, f32x16& p1, float alpha, float& l_reg, bf16x8& pa0, bf16x8& pa1, bf16x8& pa2, bf16x8& pa3) {
; #pragma unroll
;   for (int r = 0; r < 16; ++r) p1[r] = __builtin_amdgcn_exp2f(p1[r]);
;   float ps = 0;
; #pragma unroll
;   for (int r = 0; r < 16; ++r) ps += p0[r];
; #pragma unroll
;   for (int r = 0; r < 16; ++r) ps += p1[r];
;   { auto rr = __builtin_amdgcn_permlane32_swap(__float_as_uint(ps), __float_as_uint(ps), false, false);
;     ps = __uint_as_float(rr[0]) + __uint_as_float(rr[1]); }
;   l_reg = l_reg * alpha + ps;
;     ...
;   PK4(p0, 0, pa0); PK4(p0, 8, pa1); PK4(p1, 0, pa2); PK4(p1, 8, pa3);
;     ...
; }
; __device__ __forceinline__ void qkt(f32x16& p0, f32x16& p1, const bf16_t* Ks, const bf16x8* qr, const f32x16& negm, int r32, int hi) {
;   p0 = negm; p1 = negm;
; #pragma unroll
;   for (int d0 = 0; d0 < 6; ++d0) { int cb = (d0 * 16 + hi * 8) * 2;
;     bf16x8 b0 = *reinterpret_cast<const bf16x8*>((const char*)Ks + KSWZ(r32, cb));
;     bf16x8 b1 = *reinterpret_cast<const bf16x8*>((const char*)Ks + KSWZ(32 + r32, cb));
;     p0 = __builtin_amdgcn_mfma_f32_32x32x16_bf16(b0, qr[d0], p0, 0, 0, 0);
;     p1 = __builtin_amdgcn_mfma_f32_32x32x16_bf16(b1, qr[d0], p1, 0, 0, 0); }
; }
.Lat_rr_4:
	s_waitcnt lgkmcnt(0)
	s_barrier
	ds_read_b128 v[198:201], v142 offset:32768
	ds_read_b128 v[202:205], v142 offset:40960
	ds_read_b128 v[206:209], v143 offset:32768
	ds_read_b128 v[210:213], v143 offset:40960
	s_add_i32 m0, s6, 16384
	s_mov_b64 exec, s[20:21]
	global_load_lds_dwordx4 v146, s[14:15]
	s_add_i32 m0, s6, 17408
	s_mov_b64 exec, s[22:23]
	global_load_lds_dwordx4 v147, s[14:15]
	s_add_i32 m0, s7, 49152
	s_mov_b64 exec, -1
	global_load_lds_dwordx4 v149, s[14:15]
	v_add_u32_e32 v146, v146, v148
	v_add_u32_e32 v147, v147, v181
	v_add_u32_e32 v149, 0x38000, v149
	v_mfma_f32_32x32x16_bf16 v[34:49], v[182:185], v[114:117], v[98:113]
	ds_read_b128 v[182:185], v144 offset:32768
	v_exp_f32_e32 v82, v82
	v_exp_f32_e32 v83, v83
	v_exp_f32_e32 v84, v84
	v_exp_f32_e32 v85, v85
	v_exp_f32_e32 v86, v86
	v_mfma_f32_32x32x16_bf16 v[50:65], v[186:189], v[114:117], v[98:113]
	ds_read_b128 v[186:189], v144 offset:40960
	v_exp_f32_e32 v87, v87
	v_exp_f32_e32 v88, v88
	v_exp_f32_e32 v89, v89
	v_exp_f32_e32 v90, v90
	v_exp_f32_e32 v91, v91
	v_mfma_f32_32x32x16_bf16 v[34:49], v[190:193], v[118:121], v[34:49]
	ds_read_b128 v[190:193], v145 offset:32768
	v_exp_f32_e32 v92, v92
	v_exp_f32_e32 v93, v93
	v_exp_f32_e32 v94, v94
	v_exp_f32_e32 v95, v95
	v_exp_f32_e32 v96, v96
	v_mfma_f32_32x32x16_bf16 v[50:65], v[194:197], v[118:121], v[50:65]
	ds_read_b128 v[194:197], v145 offset:40960
	v_exp_f32_e32 v97, v97
	v_cvt_pk_bf16_f32 v158, v66, v67
	v_cvt_pk_bf16_f32 v159, v68, v69
	v_cvt_pk_bf16_f32 v160, v70, v71
	v_cvt_pk_bf16_f32 v161, v72, v73
	s_waitcnt lgkmcnt(6)
	v_mfma_f32_32x32x16_bf16 v[34:49], v[198:201], v[122:125], v[34:49]
	ds_read_b64_tr_b16 v[198:199], v150 offset:24576
	ds_read_b64_tr_b16 v[200:201], v150 offset:26624
	v_cvt_pk_bf16_f32 v162, v74, v75
	v_cvt_pk_bf16_f32 v163, v76, v77
	v_cvt_pk_bf16_f32 v164, v78, v79
	v_cvt_pk_bf16_f32 v165, v80, v81
	v_permlane32_swap_b32_e32 v158, v160
	v_mfma_f32_32x32x16_bf16 v[50:65], v[202:205], v[122:125], v[50:65]
	ds_read_b64_tr_b16 v[202:203], v150 offset:25088
	ds_read_b64_tr_b16 v[204:205], v150 offset:27136
	v_permlane32_swap_b32_e32 v159, v161
	v_permlane32_swap_b32_e32 v162, v164
	v_permlane32_swap_b32_e32 v163, v165
	v_add_f32_e32 v214, v214, v82
	v_add_f32_e32 v215, v215, v83
	s_waitcnt lgkmcnt(8)
	v_mfma_f32_32x32x16_bf16 v[34:49], v[206:209], v[126:129], v[34:49]
	ds_read_b64_tr_b16 v[206:207], v150 offset:28672
	ds_read_b64_tr_b16 v[208:209], v150 offset:30720
	v_add_f32_e32 v216, v216, v84
	v_add_f32_e32 v217, v217, v85
	v_add_f32_e32 v214, v214, v86
	v_add_f32_e32 v215, v215, v87
	v_add_f32_e32 v216, v216, v88
	v_mfma_f32_32x32x16_bf16 v[50:65], v[210:213], v[126:129], v[50:65]
	ds_read_b64_tr_b16 v[210:211], v150 offset:29184
	ds_read_b64_tr_b16 v[212:213], v150 offset:31232
	v_add_f32_e32 v217, v217, v89
	v_add_f32_e32 v214, v214, v90
	v_add_f32_e32 v215, v215, v91
	v_add_f32_e32 v216, v216, v92
	v_add_f32_e32 v217, v217, v93
	s_waitcnt lgkmcnt(10)
	v_mfma_f32_32x32x16_bf16 v[34:49], v[182:185], v[130:133], v[34:49]
	ds_read_b64_tr_b16 v[182:183], v150 offset:16384
	ds_read_b64_tr_b16 v[184:185], v150 offset:18432
	v_add_f32_e32 v214, v214, v94
	v_add_f32_e32 v215, v215, v95
	v_add_f32_e32 v216, v216, v96
	v_add_f32_e32 v217, v217, v97
	v_add_f32_e32 v214, v214, v215
	v_mfma_f32_32x32x16_bf16 v[50:65], v[186:189], v[130:133], v[50:65]
	ds_read_b64_tr_b16 v[186:187], v150 offset:16896
	ds_read_b64_tr_b16 v[188:189], v150 offset:18944
	v_add_f32_e32 v216, v216, v217
	v_add_f32_e32 v214, v214, v216
	v_add_f32_e32 v174, v174, v214
	v_cvt_pk_bf16_f32 v166, v82, v83
	v_cvt_pk_bf16_f32 v167, v84, v85
	s_waitcnt lgkmcnt(12)
	v_mfma_f32_32x32x16_bf16 v[34:49], v[190:193], v[134:137], v[34:49]
	ds_read_b64_tr_b16 v[190:191], v150 offset:20480
	ds_read_b64_tr_b16 v[192:193], v150 offset:22528
	v_cvt_pk_bf16_f32 v168, v86, v87
	v_cvt_pk_bf16_f32 v169, v88, v89
	v_cvt_pk_bf16_f32 v170, v90, v91
	v_cvt_pk_bf16_f32 v171, v92, v93
	v_cvt_pk_bf16_f32 v172, v94, v95
	v_mfma_f32_32x32x16_bf16 v[50:65], v[194:197], v[134:137], v[50:65]
	ds_read_b64_tr_b16 v[194:195], v150 offset:20992
	s_waitcnt lgkmcnt(14)
	ds_read_b64_tr_b16 v[196:197], v150 offset:23040
	v_cvt_pk_bf16_f32 v173, v96, v97
	v_permlane32_swap_b32_e32 v166, v168
	v_permlane32_swap_b32_e32 v167, v169
	v_permlane32_swap_b32_e32 v170, v172
	v_permlane32_swap_b32_e32 v171, v173
	s_waitcnt lgkmcnt(4)
	v_mfma_f32_32x32x16_bf16 v[2:17], v[158:161], v[182:185], v[2:17]
	ds_read_b128 v[182:185], v140 offset:49152
	v_max3_f32 v177, v34, v35, v36
	v_max3_f32 v178, v37, v38, v39
	v_max3_f32 v177, v177, v40, v41
	v_mfma_f32_32x32x16_bf16 v[18:33], v[158:161], v[186:189], v[18:33]
	ds_read_b128 v[186:189], v140 offset:57344
	v_max3_f32 v178, v178, v42, v43
	v_max3_f32 v177, v177, v44, v45
	v_max3_f32 v178, v178, v46, v47
	v_max3_f32 v177, v177, v48, v49
	v_max3_f32 v178, v178, v50, v51
	v_max3_f32 v177, v177, v52, v53
	s_waitcnt lgkmcnt(2)
	v_mfma_f32_32x32x16_bf16 v[2:17], v[162:165], v[190:193], v[2:17]
	ds_read_b128 v[190:193], v141 offset:49152
	v_max3_f32 v178, v178, v54, v55
	v_max3_f32 v177, v177, v56, v57
	v_max3_f32 v178, v178, v58, v59
	v_max3_f32 v177, v177, v60, v61
	v_max3_f32 v178, v178, v62, v63
	v_max3_f32 v177, v177, v64, v65
	v_mfma_f32_32x32x16_bf16 v[18:33], v[162:165], v[194:197], v[18:33]
	ds_read_b128 v[194:197], v141 offset:57344
	v_max_f32_e32 v177, v177, v178
	v_mov_b32_e32 v178, v177
	s_nop 1
	v_permlane32_swap_b32_e32 v177, v178
	v_max_f32_e32 v177, v177, v178
	v_cmp_ge_f32_e32 vcc, 0x4138aa3b, v177
	s_cmp_eq_u64 vcc, exec
	s_cbranch_scc0 .Lat_rare1_6

; template <bool FIRST> __device__ __forceinline__ void partialSM(f32x16& p0, f32x16& p1, float& mhat, f32x16& negm, float& alpha) {
;   float pa = fmaxf(fmaxf(p0[0], p0[1]), p1[0]), pb = fmaxf(fmaxf(p0[2], p0[3]), p1[1]); pa = fmaxf(fmaxf(pa, p1[2]), p1[3]);
; #pragma unroll
;   for (int r = 4; r < 16; r += 4) { pa = fmaxf(fmaxf(pa, p0[r]), p0[r + 1]); pb = fmaxf(fmaxf(pb, p0[r + 2]), p0[r + 3]); pa = fmaxf(fmaxf(pa, p1[r]), p1[r + 1]); pb = fmaxf(fmaxf(pb, p1[r + 2]), p1[r + 3]); }
;   float pmax = fmaxf(pa, pb);
;   { auto rr = __builtin_amdgcn_permlane32_swap(__float_as_uint(pmax), __float_as_uint(pmax), false, false);
;     pmax = fmaxf(__uint_as_float(rr[0]), __uint_as_float(rr[1])); }
;   if (!FIRST && __builtin_expect(__all(pmax <= THRL), 1)) { alpha = 1.f; }
;   else { const float d = FIRST ? pmax : fmaxf(pmax, 0.f); mhat += d; alpha = FIRST ? 1.f : __builtin_amdgcn_exp2f(-d);
; #pragma unroll
;     for (int r = 0; r < 16; ++r) { p0[r] -= d; p1[r] -= d; }
; #pragma unroll
;     for (int r = 0; r < 16; ++r) negm[r] = -mhat; }
; #pragma unroll
;   for (int r = 0; r < 16; ++r) p0[r] = __builtin_amdgcn_exp2f(p0[r]);
; }
; __device__ __forceinline__ void finishSM(f32x16& p0, f32x16& p1, float alpha, float& l_reg, bf16x8& pa0, bf16x8& pa1, bf16x8& pa2, bf16x8& pa3) {
; #pragma unroll
;   for (int r = 0; r < 16; ++r) p1[r] = __builtin_amdgcn_exp2f(p1[r]);
;   float ps = 0;
; #pragma unroll
;   for (int r = 0; r < 16; ++r) ps += p0[r];
; #pragma unroll
;   for (int r = 0; r < 16; ++r) ps += p1[r];
;   { auto rr = __builtin_amdgcn_permlane32_swap(__float_as_uint(ps), __float_as_uint(ps), false, false);
;     ps = __uint_as_float(rr[0]) + __uint_as_float(rr[1]); }
;   l_reg = l_reg * alpha + ps;
;     ...
;   PK4(p0, 0, pa0); PK4(p0, 8, pa1); PK4(p1, 0, pa2); PK4(p1, 8, pa3);
;     ...
; }
; __device__ __forceinline__ void qkt(f32x16& p0, f32x16& p1, const bf16_t* Ks, const bf16x8* qr, const f32x16& negm, int r32, int hi) {
;   p0 = negm; p1 = negm;
; #pragma unroll
;   for (int d0 = 0; d0 < 6; ++d0) { int cb = (d0 * 16 + hi * 8) * 2;
;     bf16x8 b0 = *reinterpret_cast<const bf16x8*>((const char*)Ks + KSWZ(r32, cb));
;     bf16x8 b1 = *reinterpret_cast<const bf16x8*>((const char*)Ks + KSWZ(32 + r32, cb));
;     p0 = __builtin_amdgcn_mfma_f32_32x32x16_bf16(b0, qr[d0], p0, 0, 0, 0);
;     p1 = __builtin_amdgcn_mfma_f32_32x32x16_bf16(b1, qr[d0], p1, 0, 0, 0); }
; }
.Lat_rr_8:
	s_waitcnt lgkmcnt(0)
	s_barrier
	ds_read_b128 v[198:201], v142 offset:49152
	ds_read_b128 v[202:205], v142 offset:57344
	ds_read_b128 v[206:209], v143 offset:49152
	ds_read_b128 v[210:213], v143 offset:57344
	s_add_i32 m0, s6, 32768
	s_mov_b64 exec, s[20:21]
	global_load_lds_dwordx4 v146, s[14:15]
	s_add_i32 m0, s6, 33792
	s_mov_b64 exec, s[22:23]
	global_load_lds_dwordx4 v147, s[14:15]
	s_add_i32 m0, s7, 0
	s_mov_b64 exec, -1
	global_load_lds_dwordx4 v149, s[14:15]
	v_add_u32_e32 v146, v146, v148
	v_add_u32_e32 v147, v147, v181
	v_add_u32_e32 v149, 0x38000, v149
	v_mfma_f32_32x32x16_bf16 v[66:81], v[182:185], v[114:117], v[98:113]
	ds_read_b128 v[182:185], v144 offset:49152
	v_exp_f32_e32 v50, v50
	v_exp_f32_e32 v51, v51
	v_exp_f32_e32 v52, v52
	v_exp_f32_e32 v53, v53
	v_exp_f32_e32 v54, v54
	v_mfma_f32_32x32x16_bf16 v[82:97], v[186:189], v[114:117], v[98:113]
	ds_read_b128 v[186:189], v144 offset:57344
	v_exp_f32_e32 v55, v55
	v_exp_f32_e32 v56, v56
	v_exp_f32_e32 v57, v57
	v_exp_f32_e32 v58, v58
	v_exp_f32_e32 v59, v59
	v_mfma_f32_32x32x16_bf16 v[66:81], v[190:193], v[118:121], v[66:81]
	ds_read_b128 v[190:193], v145 offset:49152
	v_exp_f32_e32 v60, v60
	v_exp_f32_e32 v61, v61
	v_exp_f32_e32 v62, v62
	v_exp_f32_e32 v63, v63
	v_exp_f32_e32 v64, v64
	v_mfma_f32_32x32x16_bf16 v[82:97], v[194:197], v[118:121], v[82:97]
	ds_read_b128 v[194:197], v145 offset:57344
	v_exp_f32_e32 v65, v65
	v_cvt_pk_bf16_f32 v158, v34, v35
	v_cvt_pk_bf16_f32 v159, v36, v37
	v_cvt_pk_bf16_f32 v160, v38, v39
	v_cvt_pk_bf16_f32 v161, v40, v41
	s_waitcnt lgkmcnt(6)
	v_mfma_f32_32x32x16_bf16 v[66:81], v[198:201], v[122:125], v[66:81]
	ds_read_b64_tr_b16 v[198:199], v150 offset:40960
	ds_read_b64_tr_b16 v[200:201], v150 offset:43008
	v_cvt_pk_bf16_f32 v162, v42, v43
	v_cvt_pk_bf16_f32 v163, v44, v45
	v_cvt_pk_bf16_f32 v164, v46, v47
	v_cvt_pk_bf16_f32 v165, v48, v49
	v_permlane32_swap_b32_e32 v158, v160
	v_mfma_f32_32x32x16_bf16 v[82:97], v[202:205], v[122:125], v[82:97]
	ds_read_b64_tr_b16 v[202:203], v150 offset:41472
	ds_read_b64_tr_b16 v[204:205], v150 offset:43520
	v_permlane32_swap_b32_e32 v159, v161
	v_permlane32_swap_b32_e32 v162, v164
	v_permlane32_swap_b32_e32 v163, v165
	v_add_f32_e32 v214, v214, v50
	v_add_f32_e32 v215, v215, v51
	s_waitcnt lgkmcnt(8)
	v_mfma_f32_32x32x16_bf16 v[66:81], v[206:209], v[126:129], v[66:81]
	ds_read_b64_tr_b16 v[206:207], v150 offset:45056
	ds_read_b64_tr_b16 v[208:209], v150 offset:47104
	v_add_f32_e32 v216, v216, v52
	v_add_f32_e32 v217, v217, v53
	v_add_f32_e32 v214, v214, v54
	v_add_f32_e32 v215, v215, v55
	v_add_f32_e32 v216, v216, v56
	v_mfma_f32_32x32x16_bf16 v[82:97], v[210:213], v[126:129], v[82:97]
	ds_read_b64_tr_b16 v[210:211], v150 offset:45568
	ds_read_b64_tr_b16 v[212:213], v150 offset:47616
	v_add_f32_e32 v217, v217, v57
	v_add_f32_e32 v214, v214, v58
	v_add_f32_e32 v215, v215, v59
	v_add_f32_e32 v216, v216, v60
	v_add_f32_e32 v217, v217, v61
	s_waitcnt lgkmcnt(10)
	v_mfma_f32_32x32x16_bf16 v[66:81], v[182:185], v[130:133], v[66:81]
	ds_read_b64_tr_b16 v[182:183], v150 offset:32768
	ds_read_b64_tr_b16 v[184:185], v150 offset:34816
	v_add_f32_e32 v214, v214, v62
	v_add_f32_e32 v215, v215, v63
	v_add_f32_e32 v216, v216, v64
	v_add_f32_e32 v217, v217, v65
	v_add_f32_e32 v214, v214, v215
	v_mfma_f32_32x32x16_bf16 v[82:97], v[186:189], v[130:133], v[82:97]
	ds_read_b64_tr_b16 v[186:187], v150 offset:33280
	ds_read_b64_tr_b16 v[188:189], v150 offset:35328
	v_add_f32_e32 v216, v216, v217
	v_add_f32_e32 v214, v214, v216
	v_add_f32_e32 v174, v174, v214
	v_cvt_pk_bf16_f32 v166, v50, v51
	v_cvt_pk_bf16_f32 v167, v52, v53
	s_waitcnt lgkmcnt(12)
	v_mfma_f32_32x32x16_bf16 v[66:81], v[190:193], v[134:137], v[66:81]
	ds_read_b64_tr_b16 v[190:191], v150 offset:36864
	ds_read_b64_tr_b16 v[192:193], v150 offset:38912
	v_cvt_pk_bf16_f32 v168, v54, v55
	v_cvt_pk_bf16_f32 v169, v56, v57
	v_cvt_pk_bf16_f32 v170, v58, v59
	v_cvt_pk_bf16_f32 v171, v60, v61
	v_cvt_pk_bf16_f32 v172, v62, v63
	v_mfma_f32_32x32x16_bf16 v[82:97], v[194:197], v[134:137], v[82:97]
	ds_read_b64_tr_b16 v[194:195], v150 offset:37376
	s_waitcnt lgkmcnt(14)
	ds_read_b64_tr_b16 v[196:197], v150 offset:39424
	v_cvt_pk_bf16_f32 v173, v64, v65
	v_permlane32_swap_b32_e32 v166, v168
	v_permlane32_swap_b32_e32 v167, v169
	v_permlane32_swap_b32_e32 v170, v172
	v_permlane32_swap_b32_e32 v171, v173
	s_waitcnt lgkmcnt(4)
	v_mfma_f32_32x32x16_bf16 v[2:17], v[158:161], v[182:185], v[2:17]
	ds_read_b128 v[182:185], v140 offset:0
	v_max3_f32 v177, v66, v67, v68
	v_max3_f32 v178, v69, v70, v71
	v_max3_f32 v177, v177, v72, v73
	v_mfma_f32_32x32x16_bf16 v[18:33], v[158:161], v[186:189], v[18:33]
	ds_read_b128 v[186:189], v140 offset:8192
	v_max3_f32 v178, v178, v74, v75
	v_max3_f32 v177, v177, v76, v77
	v_max3_f32 v178, v178, v78, v79
	v_max3_f32 v177, v177, v80, v81
	v_max3_f32 v178, v178, v82, v83
	v_max3_f32 v177, v177, v84, v85
	s_waitcnt lgkmcnt(2)
	v_mfma_f32_32x32x16_bf16 v[2:17], v[162:165], v[190:193], v[2:17]
	ds_read_b128 v[190:193], v141 offset:0
	v_max3_f32 v178, v178, v86, v87
	v_max3_f32 v177, v177, v88, v89
	v_max3_f32 v178, v178, v90, v91
	v_max3_f32 v177, v177, v92, v93
	v_max3_f32 v178, v178, v94, v95
	v_max3_f32 v177, v177, v96, v97
	v_mfma_f32_32x32x16_bf16 v[18:33], v[162:165], v[194:197], v[18:33]
	ds_read_b128 v[194:197], v141 offset:8192
	v_max_f32_e32 v177, v177, v178
	v_mov_b32_e32 v178, v177
	s_nop 1
	v_permlane32_swap_b32_e32 v177, v178
	v_max_f32_e32 v177, v177, v178
	v_cmp_ge_f32_e32 vcc, 0x4138aa3b, v177
	s_cmp_eq_u64 vcc, exec
	s_cbranch_scc0 .Lat_rare1_10

; template <bool FIRST> __device__ __forceinline__ void partialSM(f32x16& p0, f32x16& p1, float& mhat, f32x16& negm, float& alpha) {
;   float pa = fmaxf(fmaxf(p0[0], p0[1]), p1[0]), pb = fmaxf(fmaxf(p0[2], p0[3]), p1[1]); pa = fmaxf(fmaxf(pa, p1[2]), p1[3]);
; #pragma unroll
;   for (int r = 4; r < 16; r += 4) { pa = fmaxf(fmaxf(pa, p0[r]), p0[r + 1]); pb = fmaxf(fmaxf(pb, p0[r + 2]), p0[r + 3]); pa = fmaxf(fmaxf(pa, p1[r]), p1[r + 1]); pb = fmaxf(fmaxf(pb, p1[r + 2]), p1[r + 3]); }
;   float pmax = fmaxf(pa, pb);
;   { auto rr = __builtin_amdgcn_permlane32_swap(__float_as_uint(pmax), __float_as_uint(pmax), false, false);
;     pmax = fmaxf(__uint_as_float(rr[0]), __uint_as_float(rr[1])); }
;   if (!FIRST && __builtin_expect(__all(pmax <= THRL), 1)) { alpha = 1.f; }
;   else { const float d = FIRST ? pmax : fmaxf(pmax, 0.f); mhat += d; alpha = FIRST ? 1.f : __builtin_amdgcn_exp2f(-d);
; #pragma unroll
;     for (int r = 0; r < 16; ++r) { p0[r] -= d; p1[r] -= d; }
; #pragma unroll
;     for (int r = 0; r < 16; ++r) negm[r] = -mhat; }
; #pragma unroll
;   for (int r = 0; r < 16; ++r) p0[r] = __builtin_amdgcn_exp2f(p0[r]);
; }
; __device__ __forceinline__ void finishSM(f32x16& p0, f32x16& p1, float alpha, float& l_reg, bf16x8& pa0, bf16x8& pa1, bf16x8& pa2, bf16x8& pa3) {
; #pragma unroll
;   for (int r = 0; r < 16; ++r) p1[r] = __builtin_amdgcn_exp2f(p1[r]);
;   float ps = 0;
; #pragma unroll
;   for (int r = 0; r < 16; ++r) ps += p0[r];
; #pragma unroll
;   for (int r = 0; r < 16; ++r) ps += p1[r];
;   { auto rr = __builtin_amdgcn_permlane32_swap(__float_as_uint(ps), __float_as_uint(ps), false, false);
;     ps = __uint_as_float(rr[0]) + __uint_as_float(rr[1]); }
;   l_reg = l_reg * alpha + ps;
;     ...
;   PK4(p0, 0, pa0); PK4(p0, 8, pa1); PK4(p1, 0, pa2); PK4(p1, 8, pa3);
;     ...
; }
; __device__ __forceinline__ void qkt(f32x16& p0, f32x16& p1, const bf16_t* Ks, const bf16x8* qr, const f32x16& negm, int r32, int hi) {
;   p0 = negm; p1 = negm;
; #pragma unroll
;   for (int d0 = 0; d0 < 6; ++d0) { int cb = (d0 * 16 + hi * 8) * 2;
;     bf16x8 b0 = *reinterpret_cast<const bf16x8*>((const char*)Ks + KSWZ(r32, cb));
;     bf16x8 b1 = *reinterpret_cast<const bf16x8*>((const char*)Ks + KSWZ(32 + r32, cb));
;     p0 = __builtin_amdgcn_mfma_f32_32x32x16_bf16(b0, qr[d0], p0, 0, 0, 0);
;     p1 = __builtin_amdgcn_mfma_f32_32x32x16_bf16(b1, qr[d0], p1, 0, 0, 0); }
; }
.Lat_rr_12:
	s_waitcnt lgkmcnt(0)
	s_barrier
	ds_read_b128 v[198:201], v142 offset:0
	ds_read_b128 v[202:205], v142 offset:8192
	ds_read_b128 v[206:209], v143 offset:0
	ds_read_b128 v[210:213], v143 offset:8192
	s_add_i32 m0, s6, 49152
	s_mov_b64 exec, s[20:21]
	global_load_lds_dwordx4 v146, s[14:15]
	s_add_i32 m0, s6, 50176
	s_mov_b64 exec, s[22:23]
	global_load_lds_dwordx4 v147, s[14:15]
	s_add_i32 m0, s7, 16384
	s_mov_b64 exec, -1
	global_load_lds_dwordx4 v149, s[14:15]
	v_add_u32_e32 v146, v146, v148
	v_add_u32_e32 v147, v147, v181
	v_add_u32_e32 v149, 0x38000, v149
	v_mfma_f32_32x32x16_bf16 v[34:49], v[182:185], v[114:117], v[98:113]
	ds_read_b128 v[182:185], v144 offset:0
	v_exp_f32_e32 v82, v82
	v_exp_f32_e32 v83, v83
	v_exp_f32_e32 v84, v84
	v_exp_f32_e32 v85, v85
	v_exp_f32_e32 v86, v86
	v_mfma_f32_32x32x16_bf16 v[50:65], v[186:189], v[114:117], v[98:113]
	ds_read_b128 v[186:189], v144 offset:8192
	v_exp_f32_e32 v87, v87
	v_exp_f32_e32 v88, v88
	v_exp_f32_e32 v89, v89
	v_exp_f32_e32 v90, v90
	v_exp_f32_e32 v91, v91
	v_mfma_f32_32x32x16_bf16 v[34:49], v[190:193], v[118:121], v[34:49]
	ds_read_b128 v[190:193], v145 offset:0
	v_exp_f32_e32 v92, v92
	v_exp_f32_e32 v93, v93
	v_exp_f32_e32 v94, v94
	v_exp_f32_e32 v95, v95
	v_exp_f32_e32 v96, v96
	v_mfma_f32_32x32x16_bf16 v[50:65], v[194:197], v[118:121], v[50:65]
	ds_read_b128 v[194:197], v145 offset:8192
	v_exp_f32_e32 v97, v97
	v_cvt_pk_bf16_f32 v158, v66, v67
	v_cvt_pk_bf16_f32 v159, v68, v69
	v_cvt_pk_bf16_f32 v160, v70, v71
	v_cvt_pk_bf16_f32 v161, v72, v73
	s_waitcnt lgkmcnt(6)
	v_mfma_f32_32x32x16_bf16 v[34:49], v[198:201], v[122:125], v[34:49]
	ds_read_b64_tr_b16 v[198:199], v150 offset:57344
	ds_read_b64_tr_b16 v[200:201], v150 offset:59392
	v_cvt_pk_bf16_f32 v162, v74, v75
	v_cvt_pk_bf16_f32 v163, v76, v77
	v_cvt_pk_bf16_f32 v164, v78, v79
	v_cvt_pk_bf16_f32 v165, v80, v81
	v_permlane32_swap_b32_e32 v158, v160
	v_mfma_f32_32x32x16_bf16 v[50:65], v[202:205], v[122:125], v[50:65]
	ds_read_b64_tr_b16 v[202:203], v150 offset:57856
	ds_read_b64_tr_b16 v[204:205], v150 offset:59904
	v_permlane32_swap_b32_e32 v159, v161
	v_permlane32_swap_b32_e32 v162, v164
	v_permlane32_swap_b32_e32 v163, v165
	v_add_f32_e32 v214, v214, v82
	v_add_f32_e32 v215, v215, v83
	s_waitcnt lgkmcnt(8)
	v_mfma_f32_32x32x16_bf16 v[34:49], v[206:209], v[126:129], v[34:49]
	ds_read_b64_tr_b16 v[206:207], v150 offset:61440
	ds_read_b64_tr_b16 v[208:209], v150 offset:63488
	v_add_f32_e32 v216, v216, v84
	v_add_f32_e32 v217, v217, v85
	v_add_f32_e32 v214, v214, v86
	v_add_f32_e32 v215, v215, v87
	v_add_f32_e32 v216, v216, v88
	v_mfma_f32_32x32x16_bf16 v[50:65], v[210:213], v[126:129], v[50:65]
	ds_read_b64_tr_b16 v[210:211], v150 offset:61952
	ds_read_b64_tr_b16 v[212:213], v150 offset:64000
	v_add_f32_e32 v217, v217, v89
	v_add_f32_e32 v214, v214, v90
	v_add_f32_e32 v215, v215, v91
	v_add_f32_e32 v216, v216, v92
	v_add_f32_e32 v217, v217, v93
	s_waitcnt lgkmcnt(10)
	v_mfma_f32_32x32x16_bf16 v[34:49], v[182:185], v[130:133], v[34:49]
	ds_read_b64_tr_b16 v[182:183], v150 offset:49152
	ds_read_b64_tr_b16 v[184:185], v150 offset:51200
	v_add_f32_e32 v214, v214, v94
	v_add_f32_e32 v215, v215, v95
	v_add_f32_e32 v216, v216, v96
	v_add_f32_e32 v217, v217, v97
	v_add_f32_e32 v214, v214, v215
	v_mfma_f32_32x32x16_bf16 v[50:65], v[186:189], v[130:133], v[50:65]
	ds_read_b64_tr_b16 v[186:187], v150 offset:49664
	ds_read_b64_tr_b16 v[188:189], v150 offset:51712
	v_add_f32_e32 v216, v216, v217
	v_add_f32_e32 v214, v214, v216
	v_add_f32_e32 v174, v174, v214
	v_cvt_pk_bf16_f32 v166, v82, v83
	v_cvt_pk_bf16_f32 v167, v84, v85
	s_waitcnt lgkmcnt(12)
	v_mfma_f32_32x32x16_bf16 v[34:49], v[190:193], v[134:137], v[34:49]
	ds_read_b64_tr_b16 v[190:191], v150 offset:53248
	ds_read_b64_tr_b16 v[192:193], v150 offset:55296
	v_cvt_pk_bf16_f32 v168, v86, v87
	v_cvt_pk_bf16_f32 v169, v88, v89
	v_cvt_pk_bf16_f32 v170, v90, v91
	v_cvt_pk_bf16_f32 v171, v92, v93
	v_cvt_pk_bf16_f32 v172, v94, v95
	v_mfma_f32_32x32x16_bf16 v[50:65], v[194:197], v[134:137], v[50:65]
	ds_read_b64_tr_b16 v[194:195], v150 offset:53760
	s_waitcnt lgkmcnt(14)
	ds_read_b64_tr_b16 v[196:197], v150 offset:55808
	v_cvt_pk_bf16_f32 v173, v96, v97
	v_permlane32_swap_b32_e32 v166, v168
	v_permlane32_swap_b32_e32 v167, v169
	v_permlane32_swap_b32_e32 v170, v172
	v_permlane32_swap_b32_e32 v171, v173
	s_waitcnt lgkmcnt(4)
	v_mfma_f32_32x32x16_bf16 v[2:17], v[158:161], v[182:185], v[2:17]
	ds_read_b128 v[182:185], v140 offset:16384
	v_max3_f32 v177, v34, v35, v36
	v_max3_f32 v178, v37, v38, v39
	v_max3_f32 v177, v177, v40, v41
	v_mfma_f32_32x32x16_bf16 v[18:33], v[158:161], v[186:189], v[18:33]
	ds_read_b128 v[186:189], v140 offset:24576
	v_max3_f32 v178, v178, v42, v43
	v_max3_f32 v177, v177, v44, v45
	v_max3_f32 v178, v178, v46, v47
	v_max3_f32 v177, v177, v48, v49
	v_max3_f32 v178, v178, v50, v51
	v_max3_f32 v177, v177, v52, v53
	s_waitcnt lgkmcnt(2)
	v_mfma_f32_32x32x16_bf16 v[2:17], v[162:165], v[190:193], v[2:17]
	ds_read_b128 v[190:193], v141 offset:16384
	v_max3_f32 v178, v178, v54, v55
	v_max3_f32 v177, v177, v56, v57
	v_max3_f32 v178, v178, v58, v59
	v_max3_f32 v177, v177, v60, v61
	v_max3_f32 v178, v178, v62, v63
	v_max3_f32 v177, v177, v64, v65
	v_mfma_f32_32x32x16_bf16 v[18:33], v[162:165], v[194:197], v[18:33]
	ds_read_b128 v[194:197], v141 offset:24576
	v_max_f32_e32 v177, v177, v178
	v_mov_b32_e32 v178, v177
	s_nop 1
	v_permlane32_swap_b32_e32 v177, v178
	v_max_f32_e32 v177, v177, v178
	v_cmp_ge_f32_e32 vcc, 0x4138aa3b, v177
	s_cmp_eq_u64 vcc, exec
	s_cbranch_scc0 .Lat_rare1_14

; __device__ __forceinline__ void finishSM(f32x16& p0, f32x16& p1, float alpha, float& l_reg, bf16x8& pa0, bf16x8& pa1, bf16x8& pa2, bf16x8& pa3) {
; #pragma unroll
;   for (int r = 0; r < 16; ++r) p1[r] = __builtin_amdgcn_exp2f(p1[r]);
;   float ps = 0;
; #pragma unroll
;   for (int r = 0; r < 16; ++r) ps += p0[r];
; #pragma unroll
;   for (int r = 0; r < 16; ++r) ps += p1[r];
;   { auto rr = __builtin_amdgcn_permlane32_swap(__float_as_uint(ps), __float_as_uint(ps), false, false);
;     ps = __uint_as_float(rr[0]) + __uint_as_float(rr[1]); }
;   l_reg = l_reg * alpha + ps;
;     ...
;   PK4(p0, 0, pa0); PK4(p0, 8, pa1); PK4(p1, 0, pa2); PK4(p1, 8, pa3);
;     ...
; }
; __device__ __forceinline__ void qkt(f32x16& p0, f32x16& p1, const bf16_t* Ks, const bf16x8* qr, const f32x16& negm, int r32, int hi) {
;   p0 = negm; p1 = negm;
; #pragma unroll
;   for (int d0 = 0; d0 < 6; ++d0) { int cb = (d0 * 16 + hi * 8) * 2;
;     bf16x8 b0 = *reinterpret_cast<const bf16x8*>((const char*)Ks + KSWZ(r32, cb));
;     bf16x8 b1 = *reinterpret_cast<const bf16x8*>((const char*)Ks + KSWZ(32 + r32, cb));
;     p0 = __builtin_amdgcn_mfma_f32_32x32x16_bf16(b0, qr[d0], p0, 0, 0, 0);
;     p1 = __builtin_amdgcn_mfma_f32_32x32x16_bf16(b1, qr[d0], p1, 0, 0, 0); }
; }
; __device__ __forceinline__ int v_st(int k, int c) { const int kk = (k & ~0xC) | ((k & 4) << 1) | ((k & 8) >> 1); return ((kk >> 3) * 4 + (c >> 5)) * 512 + ((kk & 7) * 32 + (c & 31)) * 2; }
; __device__ __forceinline__ int v_rd_base(int lane) { return ((lane & 3) << 3) | (((lane >> 2) & 3) << 6) | (((lane >> 4) & 1) << 5) | (((lane >> 5) & 1) << 8); }
; template <int OFF> __device__ __forceinline__ s16x4 tr_read(int vb) {
;   s16x4 r; asm volatile("ds_read_b64_tr_b16 %0, %1 offset:%2" : "=&v"(r) : "v"(vb), "i"(OFF) : "memory"); return r;
; }
; __device__ __forceinline__ void attn_item(const bf16_t* __restrict__ Qb, const bf16_t* __restrict__ Kn, const bf16_t* __restrict__ Kr, const bf16_t* __restrict__ Vh,
;                                           const float* __restrict__ csq, bf16_t* __restrict__ Ob, int seq, char* lds) {
;     ...
;   for (int j = 1; j + 1 < NT; j += 2) {
;     STEP(pB0, pB1, alB, pA0, pA1, alA, j, true);
;     STEP(pA0, pA1, alA, pB0, pB1, alB, j + 1, true);
;   }
;   STEP(pB0, pB1, alB, pA0, pA1, alA, NT - 1, false);
.Lat_rr_16:
	s_waitcnt lgkmcnt(0)
	s_barrier
	s_add_i32 s8, s8, 1
	s_cmp_lt_u32 s8, 31
	s_cbranch_scc1 .Lat_loop
	ds_read_b128 v[198:201], v142 offset:16384
	ds_read_b128 v[202:205], v142 offset:24576
	ds_read_b128 v[206:209], v143 offset:16384
	ds_read_b128 v[210:213], v143 offset:24576
	s_add_i32 m0, s7, 32768
	s_mov_b64 exec, -1
	global_load_lds_dwordx4 v149, s[14:15]
	v_add_u32_e32 v149, 0x38000, v149
	v_mfma_f32_32x32x16_bf16 v[66:81], v[182:185], v[114:117], v[98:113]
	ds_read_b128 v[182:185], v144 offset:16384
	v_exp_f32_e32 v50, v50
	v_exp_f32_e32 v51, v51
	v_exp_f32_e32 v52, v52
	v_exp_f32_e32 v53, v53
	v_exp_f32_e32 v54, v54
	v_mfma_f32_32x32x16_bf16 v[82:97], v[186:189], v[114:117], v[98:113]
	ds_read_b128 v[186:189], v144 offset:24576
	v_exp_f32_e32 v55, v55
	v_exp_f32_e32 v56, v56
	v_exp_f32_e32 v57, v57
	v_exp_f32_e32 v58, v58
	v_exp_f32_e32 v59, v59
	v_mfma_f32_32x32x16_bf16 v[66:81], v[190:193], v[118:121], v[66:81]
	ds_read_b128 v[190:193], v145 offset:16384
	v_exp_f32_e32 v60, v60
	v_exp_f32_e32 v61, v61
	v_exp_f32_e32 v62, v62
	v_exp_f32_e32 v63, v63
	v_exp_f32_e32 v64, v64
	v_mfma_f32_32x32x16_bf16 v[82:97], v[194:197], v[118:121], v[82:97]
	ds_read_b128 v[194:197], v145 offset:24576
	v_exp_f32_e32 v65, v65
	v_cvt_pk_bf16_f32 v158, v34, v35
	v_cvt_pk_bf16_f32 v159, v36, v37
	v_cvt_pk_bf16_f32 v160, v38, v39
	v_cvt_pk_bf16_f32 v161, v40, v41
	s_waitcnt lgkmcnt(6)
	v_mfma_f32_32x32x16_bf16 v[66:81], v[198:201], v[122:125], v[66:81]
	ds_read_b64_tr_b16 v[198:199], v150 offset:8192
	ds_read_b64_tr_b16 v[200:201], v150 offset:10240
	v_cvt_pk_bf16_f32 v162, v42, v43
	v_cvt_pk_bf16_f32 v163, v44, v45
	v_cvt_pk_bf16_f32 v164, v46, v47
	v_cvt_pk_bf16_f32 v165, v48, v49
	v_permlane32_swap_b32_e32 v158, v160
	v_mfma_f32_32x32x16_bf16 v[82:97], v[202:205], v[122:125], v[82:97]
	ds_read_b64_tr_b16 v[202:203], v150 offset:8704
	ds_read_b64_tr_b16 v[204:205], v150 offset:10752
	v_permlane32_swap_b32_e32 v159, v161
	v_permlane32_swap_b32_e32 v162, v164
	v_permlane32_swap_b32_e32 v163, v165
	v_add_f32_e32 v214, v214, v50
	v_add_f32_e32 v215, v215, v51
	s_waitcnt lgkmcnt(8)
	v_mfma_f32_32x32x16_bf16 v[66:81], v[206:209], v[126:129], v[66:81]
	ds_read_b64_tr_b16 v[206:207], v150 offset:12288
	ds_read_b64_tr_b16 v[208:209], v150 offset:14336
	v_add_f32_e32 v216, v216, v52
	v_add_f32_e32 v217, v217, v53
	v_add_f32_e32 v214, v214, v54
	v_add_f32_e32 v215, v215, v55
	v_add_f32_e32 v216, v216, v56
	v_mfma_f32_32x32x16_bf16 v[82:97], v[210:213], v[126:129], v[82:97]
	ds_read_b64_tr_b16 v[210:211], v150 offset:12800
	ds_read_b64_tr_b16 v[212:213], v150 offset:14848
	v_add_f32_e32 v217, v217, v57
	v_add_f32_e32 v214, v214, v58
	v_add_f32_e32 v215, v215, v59
	v_add_f32_e32 v216, v216, v60
	v_add_f32_e32 v217, v217, v61
	s_waitcnt lgkmcnt(10)
	v_mfma_f32_32x32x16_bf16 v[66:81], v[182:185], v[130:133], v[66:81]
	ds_read_b64_tr_b16 v[182:183], v150 offset:0
	ds_read_b64_tr_b16 v[184:185], v150 offset:2048
	v_add_f32_e32 v214, v214, v62
	v_add_f32_e32 v215, v215, v63
	v_add_f32_e32 v216, v216, v64
	v_add_f32_e32 v217, v217, v65
	v_add_f32_e32 v214, v214, v215
	v_mfma_f32_32x32x16_bf16 v[82:97], v[186:189], v[130:133], v[82:97]
	ds_read_b64_tr_b16 v[186:187], v150 offset:512
	ds_read_b64_tr_b16 v[188:189], v150 offset:2560
	v_add_f32_e32 v216, v216, v217
	v_add_f32_e32 v214, v214, v216
	v_add_f32_e32 v174, v174, v214
	v_cvt_pk_bf16_f32 v166, v50, v51
	v_cvt_pk_bf16_f32 v167, v52, v53
	s_waitcnt lgkmcnt(12)
	v_mfma_f32_32x32x16_bf16 v[66:81], v[190:193], v[134:137], v[66:81]
	ds_read_b64_tr_b16 v[190:191], v150 offset:4096
	ds_read_b64_tr_b16 v[192:193], v150 offset:6144
	v_cvt_pk_bf16_f32 v168, v54, v55
	v_cvt_pk_bf16_f32 v169, v56, v57
	v_cvt_pk_bf16_f32 v170, v58, v59
	v_cvt_pk_bf16_f32 v171, v60, v61
	v_cvt_pk_bf16_f32 v172, v62, v63
	v_mfma_f32_32x32x16_bf16 v[82:97], v[194:197], v[134:137], v[82:97]
	ds_read_b64_tr_b16 v[194:195], v150 offset:4608
	s_waitcnt lgkmcnt(14)
	ds_read_b64_tr_b16 v[196:197], v150 offset:6656
	v_cvt_pk_bf16_f32 v173, v64, v65
	v_permlane32_swap_b32_e32 v166, v168
	v_permlane32_swap_b32_e32 v167, v169
	v_permlane32_swap_b32_e32 v170, v172
	v_permlane32_swap_b32_e32 v171, v173
	s_waitcnt lgkmcnt(4)
	v_mfma_f32_32x32x16_bf16 v[2:17], v[158:161], v[182:185], v[2:17]
	ds_read_b128 v[182:185], v140 offset:32768
	v_max3_f32 v177, v66, v67, v68
	v_max3_f32 v178, v69, v70, v71
	v_max3_f32 v177, v177, v72, v73
	v_mfma_f32_32x32x16_bf16 v[18:33], v[158:161], v[186:189], v[18:33]
	ds_read_b128 v[186:189], v140 offset:40960
	v_max3_f32 v178, v178, v74, v75
	v_max3_f32 v177, v177, v76, v77
	v_max3_f32 v178, v178, v78, v79
	v_max3_f32 v177, v177, v80, v81
	v_max3_f32 v178, v178, v82, v83
	v_max3_f32 v177, v177, v84, v85
	s_waitcnt lgkmcnt(2)
	v_mfma_f32_32x32x16_bf16 v[2:17], v[162:165], v[190:193], v[2:17]
	ds_read_b128 v[190:193], v141 offset:32768
	v_max3_f32 v178, v178, v86, v87
	v_max3_f32 v177, v177, v88, v89
	v_max3_f32 v178, v178, v90, v91
	v_max3_f32 v177, v177, v92, v93
	v_max3_f32 v178, v178, v94, v95
	v_max3_f32 v177, v177, v96, v97
	v_mfma_f32_32x32x16_bf16 v[18:33], v[162:165], v[194:197], v[18:33]
	ds_read_b128 v[194:197], v141 offset:40960
	v_max_f32_e32 v177, v177, v178
	v_mov_b32_e32 v178, v177
	s_nop 1
	v_permlane32_swap_b32_e32 v177, v178
	v_max_f32_e32 v177, v177, v178
	v_cmp_ge_f32_e32 vcc, 0x4138aa3b, v177
	s_cmp_eq_u64 vcc, exec
	s_cbranch_scc0 .Lat_rare1_18

; template <bool FIRST> __device__ __forceinline__ void partialSM(f32x16& p0, f32x16& p1, float& mhat, f32x16& negm, float& alpha) {
;   float pa = fmaxf(fmaxf(p0[0], p0[1]), p1[0]), pb = fmaxf(fmaxf(p0[2], p0[3]), p1[1]); pa = fmaxf(fmaxf(pa, p1[2]), p1[3]);
; #pragma unroll
;   for (int r = 4; r < 16; r += 4) { pa = fmaxf(fmaxf(pa, p0[r]), p0[r + 1]); pb = fmaxf(fmaxf(pb, p0[r + 2]), p0[r + 3]); pa = fmaxf(fmaxf(pa, p1[r]), p1[r + 1]); pb = fmaxf(fmaxf(pb, p1[r + 2]), p1[r + 3]); }
;   float pmax = fmaxf(pa, pb);
;   { auto rr = __builtin_amdgcn_permlane32_swap(__float_as_uint(pmax), __float_as_uint(pmax), false, false);
;     pmax = fmaxf(__uint_as_float(rr[0]), __uint_as_float(rr[1])); }
;   if (!FIRST && __builtin_expect(__all(pmax <= THRL), 1)) { alpha = 1.f; }
;   else { const float d = FIRST ? pmax : fmaxf(pmax, 0.f); mhat += d; alpha = FIRST ? 1.f : __builtin_amdgcn_exp2f(-d);
; #pragma unroll
;     for (int r = 0; r < 16; ++r) { p0[r] -= d; p1[r] -= d; }
; #pragma unroll
;     for (int r = 0; r < 16; ++r) negm[r] = -mhat; }
; #pragma unroll
;   for (int r = 0; r < 16; ++r) p0[r] = __builtin_amdgcn_exp2f(p0[r]);
; }
; __device__ __forceinline__ void finishSM(f32x16& p0, f32x16& p1, float alpha, float& l_reg, bf16x8& pa0, bf16x8& pa1, bf16x8& pa2, bf16x8& pa3) {
; #pragma unroll
;   for (int r = 0; r < 16; ++r) p1[r] = __builtin_amdgcn_exp2f(p1[r]);
;   float ps = 0;
; #pragma unroll
;   for (int r = 0; r < 16; ++r) ps += p0[r];
; #pragma unroll
;   for (int r = 0; r < 16; ++r) ps += p1[r];
;   { auto rr = __builtin_amdgcn_permlane32_swap(__float_as_uint(ps), __float_as_uint(ps), false, false);
;     ps = __uint_as_float(rr[0]) + __uint_as_float(rr[1]); }
;   l_reg = l_reg * alpha + ps;
;     ...
;   PK4(p0, 0, pa0); PK4(p0, 8, pa1); PK4(p1, 0, pa2); PK4(p1, 8, pa3);
;     ...
; }
; __device__ __forceinline__ void qkt(f32x16& p0, f32x16& p1, const bf16_t* Ks, const bf16x8* qr, const f32x16& negm, int r32, int hi) {
;   p0 = negm; p1 = negm;
; #pragma unroll
;   for (int d0 = 0; d0 < 6; ++d0) { int cb = (d0 * 16 + hi * 8) * 2;
;     bf16x8 b0 = *reinterpret_cast<const bf16x8*>((const char*)Ks + KSWZ(r32, cb));
;     bf16x8 b1 = *reinterpret_cast<const bf16x8*>((const char*)Ks + KSWZ(32 + r32, cb));
;     p0 = __builtin_amdgcn_mfma_f32_32x32x16_bf16(b0, qr[d0], p0, 0, 0, 0);
;     p1 = __builtin_amdgcn_mfma_f32_32x32x16_bf16(b1, qr[d0], p1, 0, 0, 0); }
; }
.Lat_rr_20:
	s_waitcnt lgkmcnt(0)
	s_barrier
	ds_read_b128 v[198:201], v142 offset:32768
	ds_read_b128 v[202:205], v142 offset:40960
	ds_read_b128 v[206:209], v143 offset:32768
	ds_read_b128 v[210:213], v143 offset:40960
	s_add_i32 m0, s7, 49152
	s_mov_b64 exec, -1
	global_load_lds_dwordx4 v149, s[14:15]
	v_add_u32_e32 v149, 0x38000, v149
	v_mfma_f32_32x32x16_bf16 v[34:49], v[182:185], v[114:117], v[98:113]
	ds_read_b128 v[182:185], v144 offset:32768
	v_exp_f32_e32 v82, v82
	v_exp_f32_e32 v83, v83
	v_exp_f32_e32 v84, v84
	v_exp_f32_e32 v85, v85
	v_exp_f32_e32 v86, v86
	v_mfma_f32_32x32x16_bf16 v[50:65], v[186:189], v[114:117], v[98:113]
	ds_read_b128 v[186:189], v144 offset:40960
	v_exp_f32_e32 v87, v87
	v_exp_f32_e32 v88, v88
	v_exp_f32_e32 v89, v89
	v_exp_f32_e32 v90, v90
	v_exp_f32_e32 v91, v91
	v_mfma_f32_32x32x16_bf16 v[34:49], v[190:193], v[118:121], v[34:49]
	ds_read_b128 v[190:193], v145 offset:32768
	v_exp_f32_e32 v92, v92
	v_exp_f32_e32 v93, v93
	v_exp_f32_e32 v94, v94
	v_exp_f32_e32 v95, v95
	v_exp_f32_e32 v96, v96
	v_mfma_f32_32x32x16_bf16 v[50:65], v[194:197], v[118:121], v[50:65]
	ds_read_b128 v[194:197], v145 offset:40960
	v_exp_f32_e32 v97, v97
	v_cvt_pk_bf16_f32 v158, v66, v67
	v_cvt_pk_bf16_f32 v159, v68, v69
	v_cvt_pk_bf16_f32 v160, v70, v71
	v_cvt_pk_bf16_f32 v161, v72, v73
	s_waitcnt lgkmcnt(6)
	v_mfma_f32_32x32x16_bf16 v[34:49], v[198:201], v[122:125], v[34:49]
	ds_read_b64_tr_b16 v[198:199], v150 offset:24576
	ds_read_b64_tr_b16 v[200:201], v150 offset:26624
	v_cvt_pk_bf16_f32 v162, v74, v75
	v_cvt_pk_bf16_f32 v163, v76, v77
	v_cvt_pk_bf16_f32 v164, v78, v79
	v_cvt_pk_bf16_f32 v165, v80, v81
	v_permlane32_swap_b32_e32 v158, v160
	v_mfma_f32_32x32x16_bf16 v[50:65], v[202:205], v[122:125], v[50:65]
	ds_read_b64_tr_b16 v[202:203], v150 offset:25088
	ds_read_b64_tr_b16 v[204:205], v150 offset:27136
	v_permlane32_swap_b32_e32 v159, v161
	v_permlane32_swap_b32_e32 v162, v164
	v_permlane32_swap_b32_e32 v163, v165
	v_add_f32_e32 v214, v214, v82
	v_add_f32_e32 v215, v215, v83
	s_waitcnt lgkmcnt(8)
	v_mfma_f32_32x32x16_bf16 v[34:49], v[206:209], v[126:129], v[34:49]
	ds_read_b64_tr_b16 v[206:207], v150 offset:28672
	ds_read_b64_tr_b16 v[208:209], v150 offset:30720
	v_add_f32_e32 v216, v216, v84
	v_add_f32_e32 v217, v217, v85
	v_add_f32_e32 v214, v214, v86
	v_add_f32_e32 v215, v215, v87
	v_add_f32_e32 v216, v216, v88
	v_mfma_f32_32x32x16_bf16 v[50:65], v[210:213], v[126:129], v[50:65]
	ds_read_b64_tr_b16 v[210:211], v150 offset:29184
	ds_read_b64_tr_b16 v[212:213], v150 offset:31232
	v_add_f32_e32 v217, v217, v89
	v_add_f32_e32 v214, v214, v90
	v_add_f32_e32 v215, v215, v91
	v_add_f32_e32 v216, v216, v92
	v_add_f32_e32 v217, v217, v93
	s_waitcnt lgkmcnt(10)
	v_mfma_f32_32x32x16_bf16 v[34:49], v[182:185], v[130:133], v[34:49]
	ds_read_b64_tr_b16 v[182:183], v150 offset:16384
	ds_read_b64_tr_b16 v[184:185], v150 offset:18432
	v_add_f32_e32 v214, v214, v94
	v_add_f32_e32 v215, v215, v95
	v_add_f32_e32 v216, v216, v96
	v_add_f32_e32 v217, v217, v97
	v_add_f32_e32 v214, v214, v215
	v_mfma_f32_32x32x16_bf16 v[50:65], v[186:189], v[130:133], v[50:65]
	ds_read_b64_tr_b16 v[186:187], v150 offset:16896
	ds_read_b64_tr_b16 v[188:189], v150 offset:18944
	v_add_f32_e32 v216, v216, v217
	v_add_f32_e32 v214, v214, v216
	v_add_f32_e32 v174, v174, v214
	v_cvt_pk_bf16_f32 v166, v82, v83
	v_cvt_pk_bf16_f32 v167, v84, v85
	s_waitcnt lgkmcnt(12)
	v_mfma_f32_32x32x16_bf16 v[34:49], v[190:193], v[134:137], v[34:49]
	ds_read_b64_tr_b16 v[190:191], v150 offset:20480
	ds_read_b64_tr_b16 v[192:193], v150 offset:22528
	v_cvt_pk_bf16_f32 v168, v86, v87
	v_cvt_pk_bf16_f32 v169, v88, v89
	v_cvt_pk_bf16_f32 v170, v90, v91
	v_cvt_pk_bf16_f32 v171, v92, v93
	v_cvt_pk_bf16_f32 v172, v94, v95
	v_mfma_f32_32x32x16_bf16 v[50:65], v[194:197], v[134:137], v[50:65]
	ds_read_b64_tr_b16 v[194:195], v150 offset:20992
	s_waitcnt lgkmcnt(14)
	ds_read_b64_tr_b16 v[196:197], v150 offset:23040
	v_cvt_pk_bf16_f32 v173, v96, v97
	v_permlane32_swap_b32_e32 v166, v168
	v_permlane32_swap_b32_e32 v167, v169
	v_permlane32_swap_b32_e32 v170, v172
	v_permlane32_swap_b32_e32 v171, v173
	s_waitcnt lgkmcnt(4)
	v_mfma_f32_32x32x16_bf16 v[2:17], v[158:161], v[182:185], v[2:17]
	ds_read_b128 v[182:185], v140 offset:49152
	v_max3_f32 v177, v34, v35, v36
	v_max3_f32 v178, v37, v38, v39
	v_max3_f32 v177, v177, v40, v41
	v_mfma_f32_32x32x16_bf16 v[18:33], v[158:161], v[186:189], v[18:33]
	ds_read_b128 v[186:189], v140 offset:57344
	v_max3_f32 v178, v178, v42, v43
	v_max3_f32 v177, v177, v44, v45
	v_max3_f32 v178, v178, v46, v47
	v_max3_f32 v177, v177, v48, v49
	v_max3_f32 v178, v178, v50, v51
	v_max3_f32 v177, v177, v52, v53
	s_waitcnt lgkmcnt(2)
	v_mfma_f32_32x32x16_bf16 v[2:17], v[162:165], v[190:193], v[2:17]
	ds_read_b128 v[190:193], v141 offset:49152
	v_max3_f32 v178, v178, v54, v55
	v_max3_f32 v177, v177, v56, v57
	v_max3_f32 v178, v178, v58, v59
	v_max3_f32 v177, v177, v60, v61
	v_max3_f32 v178, v178, v62, v63
	v_max3_f32 v177, v177, v64, v65
	v_mfma_f32_32x32x16_bf16 v[18:33], v[162:165], v[194:197], v[18:33]
	ds_read_b128 v[194:197], v141 offset:57344
	v_max_f32_e32 v177, v177, v178
	v_mov_b32_e32 v178, v177
	s_nop 1
	v_permlane32_swap_b32_e32 v177, v178
	v_max_f32_e32 v177, v177, v178
	v_cmp_ge_f32_e32 vcc, 0x4138aa3b, v177
	s_cmp_eq_u64 vcc, exec
	s_cbranch_scc0 .Lat_rare1_22

; template <bool FIRST> __device__ __forceinline__ void partialSM(f32x16& p0, f32x16& p1, float& mhat, f32x16& negm, float& alpha) {
;   float pa = fmaxf(fmaxf(p0[0], p0[1]), p1[0]), pb = fmaxf(fmaxf(p0[2], p0[3]), p1[1]); pa = fmaxf(fmaxf(pa, p1[2]), p1[3]);
; #pragma unroll
;   for (int r = 4; r < 16; r += 4) { pa = fmaxf(fmaxf(pa, p0[r]), p0[r + 1]); pb = fmaxf(fmaxf(pb, p0[r + 2]), p0[r + 3]); pa = fmaxf(fmaxf(pa, p1[r]), p1[r + 1]); pb = fmaxf(fmaxf(pb, p1[r + 2]), p1[r + 3]); }
;   float pmax = fmaxf(pa, pb);
;   { auto rr = __builtin_amdgcn_permlane32_swap(__float_as_uint(pmax), __float_as_uint(pmax), false, false);
;     pmax = fmaxf(__uint_as_float(rr[0]), __uint_as_float(rr[1])); }
;   if (!FIRST && __builtin_expect(__all(pmax <= THRL), 1)) { alpha = 1.f; }
;   else { const float d = FIRST ? pmax : fmaxf(pmax, 0.f); mhat += d; alpha = FIRST ? 1.f : __builtin_amdgcn_exp2f(-d);
; #pragma unroll
;     for (int r = 0; r < 16; ++r) { p0[r] -= d; p1[r] -= d; }
; #pragma unroll
;     for (int r = 0; r < 16; ++r) negm[r] = -mhat; }
; #pragma unroll
;   for (int r = 0; r < 16; ++r) p0[r] = __builtin_amdgcn_exp2f(p0[r]);
; }
; __device__ __forceinline__ void finishSM(f32x16& p0, f32x16& p1, float alpha, float& l_reg, bf16x8& pa0, bf16x8& pa1, bf16x8& pa2, bf16x8& pa3) {
; #pragma unroll
;   for (int r = 0; r < 16; ++r) p1[r] = __builtin_amdgcn_exp2f(p1[r]);
;   float ps = 0;
; #pragma unroll
;   for (int r = 0; r < 16; ++r) ps += p0[r];
; #pragma unroll
;   for (int r = 0; r < 16; ++r) ps += p1[r];
;   { auto rr = __builtin_amdgcn_permlane32_swap(__float_as_uint(ps), __float_as_uint(ps), false, false);
;     ps = __uint_as_float(rr[0]) + __uint_as_float(rr[1]); }
;   l_reg = l_reg * alpha + ps;
;     ...
;   PK4(p0, 0, pa0); PK4(p0, 8, pa1); PK4(p1, 0, pa2); PK4(p1, 8, pa3);
;     ...
; }
; __device__ __forceinline__ void qkt(f32x16& p0, f32x16& p1, const bf16_t* Ks, const bf16x8* qr, const f32x16& negm, int r32, int hi) {
;   p0 = negm; p1 = negm;
; #pragma unroll
;   for (int d0 = 0; d0 < 6; ++d0) { int cb = (d0 * 16 + hi * 8) * 2;
;     bf16x8 b0 = *reinterpret_cast<const bf16x8*>((const char*)Ks + KSWZ(r32, cb));
;     bf16x8 b1 = *reinterpret_cast<const bf16x8*>((const char*)Ks + KSWZ(32 + r32, cb));
;     p0 = __builtin_amdgcn_mfma_f32_32x32x16_bf16(b0, qr[d0], p0, 0, 0, 0);
;     p1 = __builtin_amdgcn_mfma_f32_32x32x16_bf16(b1, qr[d0], p1, 0, 0, 0); }
; }
.Lat_rr_24:
	s_waitcnt lgkmcnt(0)
	s_barrier
	ds_read_b128 v[198:201], v142 offset:49152
	ds_read_b128 v[202:205], v142 offset:57344
	ds_read_b128 v[206:209], v143 offset:49152
	ds_read_b128 v[210:213], v143 offset:57344
	v_mfma_f32_32x32x16_bf16 v[66:81], v[182:185], v[114:117], v[98:113]
	ds_read_b128 v[182:185], v144 offset:49152
	v_exp_f32_e32 v50, v50
	v_exp_f32_e32 v51, v51
	v_exp_f32_e32 v52, v52
	v_exp_f32_e32 v53, v53
	v_exp_f32_e32 v54, v54
	v_mfma_f32_32x32x16_bf16 v[82:97], v[186:189], v[114:117], v[98:113]
	ds_read_b128 v[186:189], v144 offset:57344
	v_exp_f32_e32 v55, v55
	v_exp_f32_e32 v56, v56
	v_exp_f32_e32 v57, v57
	v_exp_f32_e32 v58, v58
	v_exp_f32_e32 v59, v59
	v_mfma_f32_32x32x16_bf16 v[66:81], v[190:193], v[118:121], v[66:81]
	ds_read_b128 v[190:193], v145 offset:49152
	v_exp_f32_e32 v60, v60
	v_exp_f32_e32 v61, v61
	v_exp_f32_e32 v62, v62
	v_exp_f32_e32 v63, v63
	v_exp_f32_e32 v64, v64
	v_mfma_f32_32x32x16_bf16 v[82:97], v[194:197], v[118:121], v[82:97]
	ds_read_b128 v[194:197], v145 offset:57344
	v_exp_f32_e32 v65, v65
	v_cvt_pk_bf16_f32 v158, v34, v35
	v_cvt_pk_bf16_f32 v159, v36, v37
	v_cvt_pk_bf16_f32 v160, v38, v39
	v_cvt_pk_bf16_f32 v161, v40, v41
	s_waitcnt lgkmcnt(6)
	v_mfma_f32_32x32x16_bf16 v[66:81], v[198:201], v[122:125], v[66:81]
	ds_read_b64_tr_b16 v[198:199], v150 offset:40960
	ds_read_b64_tr_b16 v[200:201], v150 offset:43008
	v_cvt_pk_bf16_f32 v162, v42, v43
	v_cvt_pk_bf16_f32 v163, v44, v45
	v_cvt_pk_bf16_f32 v164, v46, v47
	v_cvt_pk_bf16_f32 v165, v48, v49
	v_permlane32_swap_b32_e32 v158, v160
	v_mfma_f32_32x32x16_bf16 v[82:97], v[202:205], v[122:125], v[82:97]
	ds_read_b64_tr_b16 v[202:203], v150 offset:41472
	ds_read_b64_tr_b16 v[204:205], v150 offset:43520
	v_permlane32_swap_b32_e32 v159, v161
	v_permlane32_swap_b32_e32 v162, v164
	v_permlane32_swap_b32_e32 v163, v165
	v_add_f32_e32 v214, v214, v50
	v_add_f32_e32 v215, v215, v51
	s_waitcnt lgkmcnt(8)
	v_mfma_f32_32x32x16_bf16 v[66:81], v[206:209], v[126:129], v[66:81]
	ds_read_b64_tr_b16 v[206:207], v150 offset:45056
	ds_read_b64_tr_b16 v[208:209], v150 offset:47104
	v_add_f32_e32 v216, v216, v52
	v_add_f32_e32 v217, v217, v53
	v_add_f32_e32 v214, v214, v54
	v_add_f32_e32 v215, v215, v55
	v_add_f32_e32 v216, v216, v56
	v_mfma_f32_32x32x16_bf16 v[82:97], v[210:213], v[126:129], v[82:97]
	ds_read_b64_tr_b16 v[210:211], v150 offset:45568
	ds_read_b64_tr_b16 v[212:213], v150 offset:47616
	v_add_f32_e32 v217, v217, v57
	v_add_f32_e32 v214, v214, v58
	v_add_f32_e32 v215, v215, v59
	v_add_f32_e32 v216, v216, v60
	v_add_f32_e32 v217, v217, v61
	s_waitcnt lgkmcnt(10)
	v_mfma_f32_32x32x16_bf16 v[66:81], v[182:185], v[130:133], v[66:81]
	ds_read_b64_tr_b16 v[182:183], v150 offset:32768
	ds_read_b64_tr_b16 v[184:185], v150 offset:34816
	v_add_f32_e32 v214, v214, v62
	v_add_f32_e32 v215, v215, v63
	v_add_f32_e32 v216, v216, v64
	v_add_f32_e32 v217, v217, v65
	v_add_f32_e32 v214, v214, v215
	v_mfma_f32_32x32x16_bf16 v[82:97], v[186:189], v[130:133], v[82:97]
	ds_read_b64_tr_b16 v[186:187], v150 offset:33280
	ds_read_b64_tr_b16 v[188:189], v150 offset:35328
	v_add_f32_e32 v216, v216, v217
	v_add_f32_e32 v214, v214, v216
	v_add_f32_e32 v174, v174, v214
	v_cvt_pk_bf16_f32 v166, v50, v51
	v_cvt_pk_bf16_f32 v167, v52, v53
	s_waitcnt lgkmcnt(12)
	v_mfma_f32_32x32x16_bf16 v[66:81], v[190:193], v[134:137], v[66:81]
	ds_read_b64_tr_b16 v[190:191], v150 offset:36864
	ds_read_b64_tr_b16 v[192:193], v150 offset:38912
	v_cvt_pk_bf16_f32 v168, v54, v55
	v_cvt_pk_bf16_f32 v169, v56, v57
	v_cvt_pk_bf16_f32 v170, v58, v59
	v_cvt_pk_bf16_f32 v171, v60, v61
	v_cvt_pk_bf16_f32 v172, v62, v63
	v_mfma_f32_32x32x16_bf16 v[82:97], v[194:197], v[134:137], v[82:97]
	ds_read_b64_tr_b16 v[194:195], v150 offset:37376
	s_waitcnt lgkmcnt(14)
	ds_read_b64_tr_b16 v[196:197], v150 offset:39424
	v_cvt_pk_bf16_f32 v173, v64, v65
	v_permlane32_swap_b32_e32 v166, v168
	v_permlane32_swap_b32_e32 v167, v169
	v_permlane32_swap_b32_e32 v170, v172
	v_permlane32_swap_b32_e32 v171, v173
	s_waitcnt lgkmcnt(4)
	v_mfma_f32_32x32x16_bf16 v[2:17], v[158:161], v[182:185], v[2:17]
	v_max3_f32 v177, v66, v67, v68
	v_max3_f32 v178, v69, v70, v71
	v_max3_f32 v177, v177, v72, v73
	v_mfma_f32_32x32x16_bf16 v[18:33], v[158:161], v[186:189], v[18:33]
	v_max3_f32 v178, v178, v74, v75
	v_max3_f32 v177, v177, v76, v77
	v_max3_f32 v178, v178, v78, v79
	v_max3_f32 v177, v177, v80, v81
	v_max3_f32 v178, v178, v82, v83
	v_max3_f32 v177, v177, v84, v85
	s_waitcnt lgkmcnt(0)
	v_mfma_f32_32x32x16_bf16 v[2:17], v[162:165], v[190:193], v[2:17]
	v_max3_f32 v178, v178, v86, v87
	v_max3_f32 v177, v177, v88, v89
	v_max3_f32 v178, v178, v90, v91
	v_max3_f32 v177, v177, v92, v93
	v_max3_f32 v178, v178, v94, v95
	v_max3_f32 v177, v177, v96, v97
	v_mfma_f32_32x32x16_bf16 v[18:33], v[162:165], v[194:197], v[18:33]
	v_max_f32_e32 v177, v177, v178
	v_mov_b32_e32 v178, v177
	s_nop 1
	v_permlane32_swap_b32_e32 v177, v178
	v_max_f32_e32 v177, v177, v178
	v_cmp_ge_f32_e32 vcc, 0x4138aa3b, v177
	s_cmp_eq_u64 vcc, exec
	s_cbranch_scc0 .Lat_rare1_26

; __device__ __forceinline__ void finishSM(f32x16& p0, f32x16& p1, float alpha, float& l_reg, bf16x8& pa0, bf16x8& pa1, bf16x8& pa2, bf16x8& pa3) {
; #pragma unroll
;   for (int r = 0; r < 16; ++r) p1[r] = __builtin_amdgcn_exp2f(p1[r]);
;   float ps = 0;
; #pragma unroll
;   for (int r = 0; r < 16; ++r) ps += p0[r];
; #pragma unroll
;   for (int r = 0; r < 16; ++r) ps += p1[r];
;   { auto rr = __builtin_amdgcn_permlane32_swap(__float_as_uint(ps), __float_as_uint(ps), false, false);
;     ps = __uint_as_float(rr[0]) + __uint_as_float(rr[1]); }
;   l_reg = l_reg * alpha + ps;
;     ...
;   PK4(p0, 0, pa0); PK4(p0, 8, pa1); PK4(p1, 0, pa2); PK4(p1, 8, pa3);
;     ...
; }
; __device__ __forceinline__ void qkt(f32x16& p0, f32x16& p1, const bf16_t* Ks, const bf16x8* qr, const f32x16& negm, int r32, int hi) {
;   p0 = negm; p1 = negm;
; #pragma unroll
;   for (int d0 = 0; d0 < 6; ++d0) { int cb = (d0 * 16 + hi * 8) * 2;
;     bf16x8 b0 = *reinterpret_cast<const bf16x8*>((const char*)Ks + KSWZ(r32, cb));
;     bf16x8 b1 = *reinterpret_cast<const bf16x8*>((const char*)Ks + KSWZ(32 + r32, cb));
;     p0 = __builtin_amdgcn_mfma_f32_32x32x16_bf16(b0, qr[d0], p0, 0, 0, 0);
;     p1 = __builtin_amdgcn_mfma_f32_32x32x16_bf16(b1, qr[d0], p1, 0, 0, 0); }
; }
; __device__ __forceinline__ int v_st(int k, int c) { const int kk = (k & ~0xC) | ((k & 4) << 1) | ((k & 8) >> 1); return ((kk >> 3) * 4 + (c >> 5)) * 512 + ((kk & 7) * 32 + (c & 31)) * 2; }
; __device__ __forceinline__ int v_rd_base(int lane) { return ((lane & 3) << 3) | (((lane >> 2) & 3) << 6) | (((lane >> 4) & 1) << 5) | (((lane >> 5) & 1) << 8); }
; template <int OFF> __device__ __forceinline__ s16x4 tr_read(int vb) {
;   s16x4 r; asm volatile("ds_read_b64_tr_b16 %0, %1 offset:%2" : "=&v"(r) : "v"(vb), "i"(OFF) : "memory"); return r;
; }
; template <int D0> __device__ __forceinline__ void pv_one(f32x16& od, int vb, bf16x8 pa0, bf16x8 pa1, bf16x8 pa2, bf16x8 pa3) {
;   const s16x4 l0 = tr_read<v_rd_off(D0, 0, 0)>(vb), h0 = tr_read<v_rd_off(D0, 0, 1)>(vb), l1 = tr_read<v_rd_off(D0, 1, 0)>(vb), h1 = tr_read<v_rd_off(D0, 1, 1)>(vb);
;   const s16x4 l2 = tr_read<v_rd_off(D0, 2, 0)>(vb), h2 = tr_read<v_rd_off(D0, 2, 1)>(vb), l3 = tr_read<v_rd_off(D0, 3, 0)>(vb), h3 = tr_read<v_rd_off(D0, 3, 1)>(vb);
;   asm volatile("s_waitcnt lgkmcnt(0)" ::: "memory"); SBAR();
;     ...
;   od = __builtin_amdgcn_mfma_f32_32x32x16_bf16(pa0, PK(l0, h0), od, 0, 0, 0);
.Lat_rr_28:
	s_barrier
	ds_read_b64_tr_b16 v[182:183], v150 offset:49152
	ds_read_b64_tr_b16 v[184:185], v150 offset:51200
	ds_read_b64_tr_b16 v[186:187], v150 offset:49664
	ds_read_b64_tr_b16 v[188:189], v150 offset:51712
	ds_read_b64_tr_b16 v[190:191], v150 offset:53248
	ds_read_b64_tr_b16 v[192:193], v150 offset:55296
	ds_read_b64_tr_b16 v[194:195], v150 offset:53760
	ds_read_b64_tr_b16 v[196:197], v150 offset:55808
	v_exp_f32_e32 v82, v82
	v_exp_f32_e32 v83, v83
	v_exp_f32_e32 v84, v84
	v_exp_f32_e32 v85, v85
	v_exp_f32_e32 v86, v86
	v_exp_f32_e32 v87, v87
	v_exp_f32_e32 v88, v88
	v_exp_f32_e32 v89, v89
	v_exp_f32_e32 v90, v90
	v_exp_f32_e32 v91, v91
	v_exp_f32_e32 v92, v92
	v_exp_f32_e32 v93, v93
	v_exp_f32_e32 v94, v94
	v_exp_f32_e32 v95, v95
	v_exp_f32_e32 v96, v96
	v_exp_f32_e32 v97, v97
	v_cvt_pk_bf16_f32 v158, v66, v67
	v_cvt_pk_bf16_f32 v159, v68, v69
	v_cvt_pk_bf16_f32 v160, v70, v71
	v_cvt_pk_bf16_f32 v161, v72, v73
	v_cvt_pk_bf16_f32 v162, v74, v75
	v_cvt_pk_bf16_f32 v163, v76, v77
	v_cvt_pk_bf16_f32 v164, v78, v79
	v_cvt_pk_bf16_f32 v165, v80, v81
	v_permlane32_swap_b32_e32 v158, v160
	v_permlane32_swap_b32_e32 v159, v161
	v_permlane32_swap_b32_e32 v162, v164
	v_permlane32_swap_b32_e32 v163, v165
	v_add_f32_e32 v214, v214, v82
	v_add_f32_e32 v215, v215, v83
	ds_read_b64_tr_b16 v[198:199], v150 offset:57344
	ds_read_b64_tr_b16 v[200:201], v150 offset:59392
	ds_read_b64_tr_b16 v[202:203], v150 offset:57856
	ds_read_b64_tr_b16 v[204:205], v150 offset:59904
	ds_read_b64_tr_b16 v[206:207], v150 offset:61440
	ds_read_b64_tr_b16 v[208:209], v150 offset:63488
	ds_read_b64_tr_b16 v[210:211], v150 offset:61952
	s_waitcnt lgkmcnt(14)
	ds_read_b64_tr_b16 v[212:213], v150 offset:64000
	v_add_f32_e32 v216, v216, v84
	v_add_f32_e32 v217, v217, v85
	v_add_f32_e32 v214, v214, v86
	v_add_f32_e32 v215, v215, v87
	v_add_f32_e32 v216, v216, v88
	v_add_f32_e32 v217, v217, v89
	v_add_f32_e32 v214, v214, v90
	v_add_f32_e32 v215, v215, v91
	v_add_f32_e32 v216, v216, v92
	v_add_f32_e32 v217, v217, v93
	v_add_f32_e32 v214, v214, v94
	v_add_f32_e32 v215, v215, v95
	v_add_f32_e32 v216, v216, v96
	v_add_f32_e32 v217, v217, v97
	v_add_f32_e32 v214, v214, v215
	v_add_f32_e32 v216, v216, v217
	v_add_f32_e32 v214, v214, v216
	v_add_f32_e32 v174, v174, v214
	v_cvt_pk_bf16_f32 v166, v82, v83
	v_cvt_pk_bf16_f32 v167, v84, v85
	v_cvt_pk_bf16_f32 v168, v86, v87
	v_cvt_pk_bf16_f32 v169, v88, v89
	v_cvt_pk_bf16_f32 v170, v90, v91
	v_cvt_pk_bf16_f32 v171, v92, v93
	v_cvt_pk_bf16_f32 v172, v94, v95
	v_cvt_pk_bf16_f32 v173, v96, v97
	v_permlane32_swap_b32_e32 v166, v168
	v_permlane32_swap_b32_e32 v167, v169
	v_permlane32_swap_b32_e32 v170, v172
	v_permlane32_swap_b32_e32 v171, v173
	s_waitcnt lgkmcnt(12)
	v_mfma_f32_32x32x16_bf16 v[2:17], v[158:161], v[182:185], v[2:17]
	v_mfma_f32_32x32x16_bf16 v[18:33], v[158:161], v[186:189], v[18:33]
	s_waitcnt lgkmcnt(8)
	v_mfma_f32_32x32x16_bf16 v[2:17], v[162:165], v[190:193], v[2:17]
	v_mfma_f32_32x32x16_bf16 v[18:33], v[162:165], v[194:197], v[18:33]
	s_waitcnt lgkmcnt(4)
	v_mfma_f32_32x32x16_bf16 v[2:17], v[166:169], v[198:201], v[2:17]
	v_mfma_f32_32x32x16_bf16 v[18:33], v[166:169], v[202:205], v[18:33]
	s_waitcnt lgkmcnt(0)
	v_mfma_f32_32x32x16_bf16 v[2:17], v[170:173], v[206:209], v[2:17]
	v_mfma_f32_32x32x16_bf16 v[18:33], v[170:173], v[210:213], v[18:33]
	s_waitcnt vmcnt(0)
	s_cmp_lg_u32 s9, 0
	s_cbranch_scc1 .Lat_rare2_30

; __global__ void __launch_bounds__(512, 2) mega(Args a_unused) {
	.amdhsa_kernel _Z4mega4Args
		.amdhsa_group_segment_fixed_size 0
		.amdhsa_private_segment_fixed_size 0
		.amdhsa_kernarg_size 552
		.amdhsa_user_sgpr_count 2
		.amdhsa_user_sgpr_dispatch_ptr 0
		.amdhsa_user_sgpr_queue_ptr 0
		.amdhsa_user_sgpr_kernarg_segment_ptr 1
		.amdhsa_user_sgpr_dispatch_id 0
		.amdhsa_user_sgpr_kernarg_preload_length 0
		.amdhsa_user_sgpr_kernarg_preload_offset 0
		.amdhsa_user_sgpr_private_segment_size 0
		.amdhsa_uses_dynamic_stack 0
		.amdhsa_enable_private_segment 0
		.amdhsa_system_sgpr_workgroup_id_x 1
		.amdhsa_system_sgpr_workgroup_id_y 0
		.amdhsa_system_sgpr_workgroup_id_z 0
		.amdhsa_system_sgpr_workgroup_info 0
		.amdhsa_system_vgpr_workitem_id 2
		.amdhsa_next_free_vgpr 256
		.amdhsa_next_free_sgpr 102
		.amdhsa_accum_offset 256
		.amdhsa_reserve_vcc 1
		.amdhsa_float_round_mode_32 0
		.amdhsa_float_round_mode_16_64 0
		.amdhsa_float_denorm_mode_32 3
		.amdhsa_float_denorm_mode_16_64 3
		.amdhsa_dx10_clamp 1
		.amdhsa_ieee_mode 1
		.amdhsa_fp16_overflow 0
		.amdhsa_tg_split 0
		.amdhsa_exception_fp_ieee_invalid_op 0
		.amdhsa_exception_fp_denorm_src 0
		.amdhsa_exception_fp_ieee_div_zero 0
		.amdhsa_exception_fp_ieee_overflow 0
		.amdhsa_exception_fp_ieee_underflow 0
		.amdhsa_exception_fp_ieee_inexact 0
		.amdhsa_exception_int_div_zero 0
	.end_amdhsa_kernel

; __global__ void __launch_bounds__(512, 2) mega(Args a_unused) {
amdhsa.kernels:
  - .agpr_count:     0
    .args:
      - .offset:         0
        .size:           296
        .value_kind:     by_value
      - .offset:         296
        .size:           4
        .value_kind:     hidden_block_count_x
      - .offset:         300
        .size:           4
        .value_kind:     hidden_block_count_y
      - .offset:         304
        .size:           4
        .value_kind:     hidden_block_count_z
      - .offset:         308
        .size:           2
        .value_kind:     hidden_group_size_x
      - .offset:         310
        .size:           2
        .value_kind:     hidden_group_size_y
      - .offset:         312
        .size:           2
        .value_kind:     hidden_group_size_z
      - .offset:         314
        .size:           2
        .value_kind:     hidden_remainder_x
      - .offset:         316
        .size:           2
        .value_kind:     hidden_remainder_y
      - .offset:         318
        .size:           2
        .value_kind:     hidden_remainder_z
      - .offset:         336
        .size:           8
        .value_kind:     hidden_global_offset_x
      - .offset:         344
        .size:           8
        .value_kind:     hidden_global_offset_y
      - .offset:         352
        .size:           8
        .value_kind:     hidden_global_offset_z
      - .offset:         360
        .size:           2
        .value_kind:     hidden_grid_dims
      - .offset:         384
        .size:           8
        .value_kind:     hidden_multigrid_sync_arg
      - .offset:         416
        .size:           4
        .value_kind:     hidden_dynamic_lds_size
    .group_segment_fixed_size: 0
    .kernarg_segment_align: 8
    .kernarg_segment_size: 552
    .language:       OpenCL C
    .language_version:
      - 2
      - 0
    .max_flat_workgroup_size: 512
    .name:           _Z4mega4Args
    .private_segment_fixed_size: 0
    .sgpr_count:     108
    .sgpr_spill_count: 88
    .symbol:         _Z4mega4Args.kd
    .uniform_work_group_size: 1
    .uses_dynamic_stack: false
    .vgpr_count:     256
    .vgpr_spill_count: 0
    .wavefront_size: 64
